# K-loops: back-edge rotation - counter updates and exit compare moved in front of the final barrier of each iteration
# baseline (speedup 1.0000x reference)
; #define PG8_STAGE(bufoff, gbase, voff) do { _Pragma("unroll") for (int _i = 0; _i < 2; ++_i) \
;         __builtin_amdgcn_global_load_lds((const unsigned*)((const char*)(gbase) + (voff)[_i]), (LAS unsigned*)(lds + (bufoff) + ldsw + _i * 8192), 16, 0, 0); } while (0)
; #define PG8_LDA(dst, b, h) do { _Pragma("unroll") for (int m = 0; m < 4; ++m) _Pragma("unroll") for (int k = 0; k < 2; ++k) dst[m][k] = *(const LAS bf16x8*)(lds + PG8_SA(b, h) + aoff + m * 2048 + k * 1024); } while (0)
; #define PG8_LDB(dst, b, h) do { _Pragma("unroll") for (int n = 0; n < 2; ++n) _Pragma("unroll") for (int k = 0; k < 2; ++k) dst[n][k] = *(const LAS bf16x8*)(lds + PG8_SB(b, h) + boff + n * 2048 + k * 1024); } while (0)
; #define PG8_MMA(ai, bj, At, Bt) do { __builtin_amdgcn_s_setprio(1); _Pragma("unroll") for (int m = 0; m < 4; ++m) _Pragma("unroll") for (int n = 0; n < 2; ++n) _Pragma("unroll") for (int k = 0; k < 2; ++k) \
;         acc[ai][bj][m][n] = __builtin_amdgcn_mfma_f32_16x16x32_bf16(Bt[n][k], At[m][k], acc[ai][bj][m][n], 0, 0, 0); __builtin_amdgcn_s_setprio(0); } while (0)
; #define PG8_WAIT_V(n) asm volatile("s_waitcnt vmcnt(" #n ")" ::: "memory")
; #define PG8_WAIT_L(n) asm volatile("s_waitcnt lgkmcnt(" #n ")" ::: "memory")
; #define PG8_BAR __builtin_amdgcn_s_barrier()
; #define PG8_SCHED __builtin_amdgcn_sched_barrier(0)
; template <class Epi, bool PERMA = false, bool DUAL = false, bool ALIGN_EPI = true, bool SP2 = true>
; __device__ __forceinline__ void gemm_phase(LAS unsigned char* lds, const Gemm g, const StaticOrder& S, const Epi& E) {
;     ...
;             const bool last = (t == nt - 2);
;             const char* a1 = cA + (size_t)(t + 1) * kstep;
;             const char* a2 = last ? nA : cA + (size_t)(t + 2) * kstep; const char* b2 = last ? nB : cB + (size_t)(t + 2) * kstep;
;             const char* a3 = a2 + kstep; const char* b3 = b2 + kstep;
;             if constexpr (SP2) {
;             PG8_LDB(B0, 0, 0); PG8_LDB(B1, 0, 1); PG8_SCHED; PG8_LDA(At, 0, 0); PG8_STAGE(PG8_SA(1, 1), a1 + hstepA, voffA);
;             PG8_WAIT_V(8); PG8_WAIT_L(0); PG8_BAR; PG8_MMA(0, 0, At, B0); PG8_MMA(0, 1, At, B1); PG8_BAR; PG8_SCHED;
;             PG8_LDA(At, 0, 1); PG8_STAGE(PG8_SB(0, 0), b2, voffB); PG8_STAGE(PG8_SB(0, 1), b2 + hstepB, voffB); PG8_STAGE(PG8_SA(0, 0), a2, voffA);
.LBB0_130:
	s_add_u32 s16, s14, 0xfff80080
	s_addc_u32 s17, s15, -1
	s_add_i32 s38, 0, 0x10000
	s_cmp_eq_u32 s37, 28
	s_cselect_b32 s19, s9, s17
	s_cselect_b32 s18, s33, s16
	s_cselect_b32 s17, s7, s36
	s_cselect_b32 s16, s34, s35
	s_add_i32 s40, 0, 0x14000
	v_add_u32_e32 v156, s38, v141
	v_add_u32_e32 v172, s40, v141
	ds_read_b128 v[144:147], v156
	ds_read_b128 v[148:151], v156 offset:1024
	ds_read_b128 v[152:155], v156 offset:2048
	ds_read_b128 v[156:159], v156 offset:3072
	ds_read_b128 v[160:163], v172
	ds_read_b128 v[164:167], v172 offset:1024
	ds_read_b128 v[168:171], v172 offset:2048
	ds_read_b128 v[172:175], v172 offset:3072
	v_lshl_add_u64 v[222:223], s[14:15], 0, v[136:137]
	s_add_i32 m0, s21, 0xc000
	ds_read_b128 v[176:179], v143
	ds_read_b128 v[180:183], v143 offset:1024
	ds_read_b128 v[184:187], v143 offset:2048
	ds_read_b128 v[188:191], v143 offset:3072
	ds_read_b128 v[206:209], v143 offset:4096
	ds_read_b128 v[210:213], v143 offset:5120
	ds_read_b128 v[214:217], v143 offset:6144
	ds_read_b128 v[218:221], v143 offset:7168
	global_load_lds_dwordx4 v[222:223], off
	v_lshl_add_u64 v[222:223], s[14:15], 0, v[138:139]
	s_add_i32 m0, s21, 0xe000
	s_nop 0
	global_load_lds_dwordx4 v[222:223], off
	s_waitcnt vmcnt(8)
	s_waitcnt lgkmcnt(0)
	s_barrier
	s_waitcnt lgkmcnt(0)
	v_mfma_f32_16x16x32_bf16 v[124:127], v[144:147], v[176:179], v[124:127]
	v_mfma_f32_16x16x32_bf16 v[120:123], v[152:155], v[176:179], v[120:123]
	v_mfma_f32_16x16x32_bf16 v[116:119], v[144:147], v[184:187], v[116:119]
	v_mfma_f32_16x16x32_bf16 v[108:111], v[152:155], v[184:187], v[108:111]
	v_mfma_f32_16x16x32_bf16 v[100:103], v[144:147], v[206:209], v[100:103]
	v_mfma_f32_16x16x32_bf16 v[92:95], v[152:155], v[206:209], v[92:95]
	v_mfma_f32_16x16x32_bf16 v[84:87], v[144:147], v[214:217], v[84:87]
	v_mfma_f32_16x16x32_bf16 v[76:79], v[152:155], v[214:217], v[76:79]
	v_mfma_f32_16x16x32_bf16 v[124:127], v[148:151], v[180:183], v[124:127]
	v_mfma_f32_16x16x32_bf16 v[120:123], v[156:159], v[180:183], v[120:123]
	v_mfma_f32_16x16x32_bf16 v[116:119], v[148:151], v[188:191], v[116:119]
	v_mfma_f32_16x16x32_bf16 v[108:111], v[156:159], v[188:191], v[108:111]
	v_mfma_f32_16x16x32_bf16 v[100:103], v[148:151], v[210:213], v[100:103]
	v_mfma_f32_16x16x32_bf16 v[92:95], v[156:159], v[210:213], v[92:95]
	v_mfma_f32_16x16x32_bf16 v[84:87], v[148:151], v[218:221], v[84:87]
	v_mfma_f32_16x16x32_bf16 v[76:79], v[156:159], v[218:221], v[76:79]
	v_mfma_f32_16x16x32_bf16 v[112:115], v[160:163], v[176:179], v[112:115]
	v_mfma_f32_16x16x32_bf16 v[104:107], v[168:171], v[176:179], v[104:107]
	v_mfma_f32_16x16x32_bf16 v[96:99], v[160:163], v[184:187], v[96:99]
	v_mfma_f32_16x16x32_bf16 v[88:91], v[168:171], v[184:187], v[88:91]
	v_mfma_f32_16x16x32_bf16 v[80:83], v[160:163], v[206:209], v[80:83]
	v_mfma_f32_16x16x32_bf16 v[72:75], v[168:171], v[206:209], v[72:75]
	v_mfma_f32_16x16x32_bf16 v[68:71], v[160:163], v[214:217], v[68:71]
	v_mfma_f32_16x16x32_bf16 v[64:67], v[168:171], v[214:217], v[64:67]
	v_mfma_f32_16x16x32_bf16 v[112:115], v[164:167], v[180:183], v[112:115]
	v_mfma_f32_16x16x32_bf16 v[104:107], v[172:175], v[180:183], v[104:107]
	v_mfma_f32_16x16x32_bf16 v[96:99], v[164:167], v[188:191], v[96:99]
	v_mfma_f32_16x16x32_bf16 v[88:91], v[172:175], v[188:191], v[88:91]
	v_mfma_f32_16x16x32_bf16 v[80:83], v[164:167], v[210:213], v[80:83]
	v_mfma_f32_16x16x32_bf16 v[72:75], v[172:175], v[210:213], v[72:75]
	v_mfma_f32_16x16x32_bf16 v[68:71], v[164:167], v[218:221], v[68:71]
	v_mfma_f32_16x16x32_bf16 v[64:67], v[172:175], v[218:221], v[64:67]
	s_barrier
	s_add_i32 s38, s38, s20
	v_lshl_add_u64 v[222:223], s[16:17], 0, v[132:133]
	s_mov_b32 m0, s38
	ds_read_b128 v[176:179], v143 offset:16384
	ds_read_b128 v[180:183], v143 offset:17408
	ds_read_b128 v[184:187], v143 offset:18432
	ds_read_b128 v[188:191], v143 offset:19456
	ds_read_b128 v[206:209], v143 offset:20480
	ds_read_b128 v[210:213], v143 offset:21504
	ds_read_b128 v[214:217], v143 offset:22528
	ds_read_b128 v[218:221], v143 offset:23552
	global_load_lds_dwordx4 v[222:223], off
	s_add_i32 m0, s38, 0x2000
	s_add_u32 s38, s16, 0x80000
	v_lshl_add_u64 v[224:225], s[16:17], 0, v[128:129]
	s_addc_u32 s39, s17, 0
	s_add_i32 s40, s40, s20
	global_load_lds_dwordx4 v[224:225], off
	v_lshl_add_u64 v[226:227], s[38:39], 0, v[132:133]
	s_mov_b32 m0, s40
	v_lshl_add_u64 v[228:229], s[18:19], 0, v[130:131]
	global_load_lds_dwordx4 v[226:227], off
	v_lshl_add_u64 v[226:227], s[38:39], 0, v[128:129]
	s_add_i32 m0, s40, 0x2000
	s_nop 0
	global_load_lds_dwordx4 v[226:227], off
	v_lshl_add_u64 v[226:227], s[18:19], 0, v[134:135]
	s_mov_b32 m0, s21
	s_nop 0
	global_load_lds_dwordx4 v[226:227], off
	s_mov_b32 m0, s22
	s_nop 0
	global_load_lds_dwordx4 v[228:229], off
	s_waitcnt vmcnt(8)
	s_waitcnt lgkmcnt(0)
	s_barrier
; #define PG8_STAGE(bufoff, gbase, voff) do { _Pragma("unroll") for (int _i = 0; _i < 2; ++_i) \
;         __builtin_amdgcn_global_load_lds((const unsigned*)((const char*)(gbase) + (voff)[_i]), (LAS unsigned*)(lds + (bufoff) + ldsw + _i * 8192), 16, 0, 0); } while (0)
; #define PG8_LDA(dst, b, h) do { _Pragma("unroll") for (int m = 0; m < 4; ++m) _Pragma("unroll") for (int k = 0; k < 2; ++k) dst[m][k] = *(const LAS bf16x8*)(lds + PG8_SA(b, h) + aoff + m * 2048 + k * 1024); } while (0)
; #define PG8_LDB(dst, b, h) do { _Pragma("unroll") for (int n = 0; n < 2; ++n) _Pragma("unroll") for (int k = 0; k < 2; ++k) dst[n][k] = *(const LAS bf16x8*)(lds + PG8_SB(b, h) + boff + n * 2048 + k * 1024); } while (0)
; #define PG8_MMA(ai, bj, At, Bt) do { __builtin_amdgcn_s_setprio(1); _Pragma("unroll") for (int m = 0; m < 4; ++m) _Pragma("unroll") for (int n = 0; n < 2; ++n) _Pragma("unroll") for (int k = 0; k < 2; ++k) \
;         acc[ai][bj][m][n] = __builtin_amdgcn_mfma_f32_16x16x32_bf16(Bt[n][k], At[m][k], acc[ai][bj][m][n], 0, 0, 0); __builtin_amdgcn_s_setprio(0); } while (0)
; #define PG8_WAIT_V(n) asm volatile("s_waitcnt vmcnt(" #n ")" ::: "memory")
; #define PG8_WAIT_L(n) asm volatile("s_waitcnt lgkmcnt(" #n ")" ::: "memory")
; #define PG8_BAR __builtin_amdgcn_s_barrier()
; #define PG8_SCHED __builtin_amdgcn_sched_barrier(0)
; template <class Epi, bool PERMA = false, bool DUAL = false, bool ALIGN_EPI = true, bool SP2 = true>
; __device__ __forceinline__ void gemm_phase(LAS unsigned char* lds, const Gemm g, const StaticOrder& S, const Epi& E) {
;     ...
;             PG8_WAIT_V(8); PG8_WAIT_L(0); PG8_BAR; PG8_MMA(1, 0, At, B0); PG8_MMA(1, 1, At, B1); PG8_BAR; PG8_SCHED;
;             PG8_LDB(B0, 1, 0); PG8_LDB(B1, 1, 1); PG8_SCHED; PG8_LDA(At, 1, 0); PG8_STAGE(PG8_SA(0, 1), a2 + hstepA, voffA);
;             PG8_WAIT_V(8); PG8_WAIT_L(0); PG8_BAR; PG8_MMA(0, 0, At, B0); PG8_MMA(0, 1, At, B1); PG8_BAR; PG8_SCHED;
	s_waitcnt lgkmcnt(0)
	v_mfma_f32_16x16x32_bf16 v[60:63], v[144:147], v[176:179], v[60:63]
	v_mfma_f32_16x16x32_bf16 v[56:59], v[152:155], v[176:179], v[56:59]
	v_mfma_f32_16x16x32_bf16 v[52:55], v[144:147], v[184:187], v[52:55]
	v_mfma_f32_16x16x32_bf16 v[44:47], v[152:155], v[184:187], v[44:47]
	v_mfma_f32_16x16x32_bf16 v[36:39], v[144:147], v[206:209], v[36:39]
	v_mfma_f32_16x16x32_bf16 v[28:31], v[152:155], v[206:209], v[28:31]
	v_mfma_f32_16x16x32_bf16 v[20:23], v[144:147], v[214:217], v[20:23]
	v_mfma_f32_16x16x32_bf16 v[12:15], v[152:155], v[214:217], v[12:15]
	v_mfma_f32_16x16x32_bf16 v[60:63], v[148:151], v[180:183], v[60:63]
	v_mfma_f32_16x16x32_bf16 v[56:59], v[156:159], v[180:183], v[56:59]
	v_mfma_f32_16x16x32_bf16 v[52:55], v[148:151], v[188:191], v[52:55]
	v_mfma_f32_16x16x32_bf16 v[44:47], v[156:159], v[188:191], v[44:47]
	v_mfma_f32_16x16x32_bf16 v[36:39], v[148:151], v[210:213], v[36:39]
	v_mfma_f32_16x16x32_bf16 v[28:31], v[156:159], v[210:213], v[28:31]
	v_mfma_f32_16x16x32_bf16 v[20:23], v[148:151], v[218:221], v[20:23]
	v_mfma_f32_16x16x32_bf16 v[12:15], v[156:159], v[218:221], v[12:15]
	v_mfma_f32_16x16x32_bf16 v[48:51], v[160:163], v[176:179], v[48:51]
	v_mfma_f32_16x16x32_bf16 v[40:43], v[168:171], v[176:179], v[40:43]
	v_mfma_f32_16x16x32_bf16 v[32:35], v[160:163], v[184:187], v[32:35]
	v_mfma_f32_16x16x32_bf16 v[24:27], v[168:171], v[184:187], v[24:27]
	v_mfma_f32_16x16x32_bf16 v[16:19], v[160:163], v[206:209], v[16:19]
	v_mfma_f32_16x16x32_bf16 v[8:11], v[168:171], v[206:209], v[8:11]
	v_mfma_f32_16x16x32_bf16 v[4:7], v[160:163], v[214:217], v[4:7]
	v_mfma_f32_16x16x32_bf16 v[0:3], v[168:171], v[214:217], v[0:3]
	v_mfma_f32_16x16x32_bf16 v[48:51], v[164:167], v[180:183], v[48:51]
	v_mfma_f32_16x16x32_bf16 v[40:43], v[172:175], v[180:183], v[40:43]
	v_mfma_f32_16x16x32_bf16 v[32:35], v[164:167], v[188:191], v[32:35]
	v_mfma_f32_16x16x32_bf16 v[24:27], v[172:175], v[188:191], v[24:27]
	v_mfma_f32_16x16x32_bf16 v[16:19], v[164:167], v[210:213], v[16:19]
	v_mfma_f32_16x16x32_bf16 v[8:11], v[172:175], v[210:213], v[8:11]
	v_mfma_f32_16x16x32_bf16 v[4:7], v[164:167], v[218:221], v[4:7]
	v_mfma_f32_16x16x32_bf16 v[0:3], v[172:175], v[218:221], v[0:3]
	s_barrier
	s_add_i32 s38, 0, 0x18000
	s_add_i32 s39, 0, 0x1c000
	v_add_u32_e32 v156, s38, v141
	v_add_u32_e32 v172, s39, v141
	ds_read_b128 v[144:147], v156
	ds_read_b128 v[148:151], v156 offset:1024
	ds_read_b128 v[152:155], v156 offset:2048
	ds_read_b128 v[156:159], v156 offset:3072
	ds_read_b128 v[160:163], v172
	ds_read_b128 v[164:167], v172 offset:1024
	ds_read_b128 v[168:171], v172 offset:2048
	ds_read_b128 v[172:175], v172 offset:3072
	s_add_u32 s18, s18, 0x80000
	s_addc_u32 s19, s19, 0
	s_mov_b32 m0, s23
	v_lshl_add_u64 v[238:239], s[18:19], 0, v[134:135]
	ds_read_b128 v[176:179], v143 offset:32768
	ds_read_b128 v[180:183], v143 offset:33792
	ds_read_b128 v[184:187], v143 offset:34816
	ds_read_b128 v[188:191], v143 offset:35840
	ds_read_b128 v[206:209], v143 offset:36864
	ds_read_b128 v[210:213], v143 offset:37888
	ds_read_b128 v[214:217], v143 offset:38912
	ds_read_b128 v[218:221], v143 offset:39936
	global_load_lds_dwordx4 v[238:239], off
	v_lshl_add_u64 v[238:239], s[18:19], 0, v[130:131]
	s_mov_b32 m0, s24
	s_nop 0
	global_load_lds_dwordx4 v[238:239], off
	s_waitcnt vmcnt(8)
	s_waitcnt lgkmcnt(0)
	s_barrier
	s_waitcnt lgkmcnt(0)
	v_mfma_f32_16x16x32_bf16 v[124:127], v[144:147], v[176:179], v[124:127]
	v_mfma_f32_16x16x32_bf16 v[120:123], v[152:155], v[176:179], v[120:123]
	v_mfma_f32_16x16x32_bf16 v[116:119], v[144:147], v[184:187], v[116:119]
	v_mfma_f32_16x16x32_bf16 v[108:111], v[152:155], v[184:187], v[108:111]
	v_mfma_f32_16x16x32_bf16 v[100:103], v[144:147], v[206:209], v[100:103]
	v_mfma_f32_16x16x32_bf16 v[92:95], v[152:155], v[206:209], v[92:95]
	v_mfma_f32_16x16x32_bf16 v[84:87], v[144:147], v[214:217], v[84:87]
	v_mfma_f32_16x16x32_bf16 v[76:79], v[152:155], v[214:217], v[76:79]
	v_mfma_f32_16x16x32_bf16 v[124:127], v[148:151], v[180:183], v[124:127]
	v_mfma_f32_16x16x32_bf16 v[120:123], v[156:159], v[180:183], v[120:123]
	v_mfma_f32_16x16x32_bf16 v[116:119], v[148:151], v[188:191], v[116:119]
	v_mfma_f32_16x16x32_bf16 v[108:111], v[156:159], v[188:191], v[108:111]
	v_mfma_f32_16x16x32_bf16 v[100:103], v[148:151], v[210:213], v[100:103]
	v_mfma_f32_16x16x32_bf16 v[92:95], v[156:159], v[210:213], v[92:95]
	v_mfma_f32_16x16x32_bf16 v[84:87], v[148:151], v[218:221], v[84:87]
	v_mfma_f32_16x16x32_bf16 v[76:79], v[156:159], v[218:221], v[76:79]
	v_mfma_f32_16x16x32_bf16 v[112:115], v[160:163], v[176:179], v[112:115]
	v_mfma_f32_16x16x32_bf16 v[104:107], v[168:171], v[176:179], v[104:107]
	v_mfma_f32_16x16x32_bf16 v[96:99], v[160:163], v[184:187], v[96:99]
	v_mfma_f32_16x16x32_bf16 v[88:91], v[168:171], v[184:187], v[88:91]
	v_mfma_f32_16x16x32_bf16 v[80:83], v[160:163], v[206:209], v[80:83]
	v_mfma_f32_16x16x32_bf16 v[72:75], v[168:171], v[206:209], v[72:75]
	v_mfma_f32_16x16x32_bf16 v[68:71], v[160:163], v[214:217], v[68:71]
	v_mfma_f32_16x16x32_bf16 v[64:67], v[168:171], v[214:217], v[64:67]
	v_mfma_f32_16x16x32_bf16 v[112:115], v[164:167], v[180:183], v[112:115]
	v_mfma_f32_16x16x32_bf16 v[104:107], v[172:175], v[180:183], v[104:107]
	v_mfma_f32_16x16x32_bf16 v[96:99], v[164:167], v[188:191], v[96:99]
	v_mfma_f32_16x16x32_bf16 v[88:91], v[172:175], v[188:191], v[88:91]
	v_mfma_f32_16x16x32_bf16 v[80:83], v[164:167], v[210:213], v[80:83]
	v_mfma_f32_16x16x32_bf16 v[72:75], v[172:175], v[210:213], v[72:75]
	v_mfma_f32_16x16x32_bf16 v[68:71], v[164:167], v[218:221], v[68:71]
	v_mfma_f32_16x16x32_bf16 v[64:67], v[172:175], v[218:221], v[64:67]
	s_barrier
; #define PG8_STAGE(bufoff, gbase, voff) do { _Pragma("unroll") for (int _i = 0; _i < 2; ++_i) \
;         __builtin_amdgcn_global_load_lds((const unsigned*)((const char*)(gbase) + (voff)[_i]), (LAS unsigned*)(lds + (bufoff) + ldsw + _i * 8192), 16, 0, 0); } while (0)
; #define PG8_LDA(dst, b, h) do { _Pragma("unroll") for (int m = 0; m < 4; ++m) _Pragma("unroll") for (int k = 0; k < 2; ++k) dst[m][k] = *(const LAS bf16x8*)(lds + PG8_SA(b, h) + aoff + m * 2048 + k * 1024); } while (0)
; #define PG8_MMA(ai, bj, At, Bt) do { __builtin_amdgcn_s_setprio(1); _Pragma("unroll") for (int m = 0; m < 4; ++m) _Pragma("unroll") for (int n = 0; n < 2; ++n) _Pragma("unroll") for (int k = 0; k < 2; ++k) \
;         acc[ai][bj][m][n] = __builtin_amdgcn_mfma_f32_16x16x32_bf16(Bt[n][k], At[m][k], acc[ai][bj][m][n], 0, 0, 0); __builtin_amdgcn_s_setprio(0); } while (0)
; #define PG8_WAIT_V(n) asm volatile("s_waitcnt vmcnt(" #n ")" ::: "memory")
; #define PG8_WAIT_L(n) asm volatile("s_waitcnt lgkmcnt(" #n ")" ::: "memory")
; #define PG8_BAR __builtin_amdgcn_s_barrier()
; #define PG8_SCHED __builtin_amdgcn_sched_barrier(0)
; template <class Epi, bool PERMA = false, bool DUAL = false, bool ALIGN_EPI = true, bool SP2 = true>
; __device__ __forceinline__ void gemm_phase(LAS unsigned char* lds, const Gemm g, const StaticOrder& S, const Epi& E) {
;     ...
;             PG8_LDA(At, 1, 1); PG8_STAGE(PG8_SB(1, 0), b3, voffB); PG8_STAGE(PG8_SB(1, 1), b3 + hstepB, voffB); PG8_STAGE(PG8_SA(1, 0), a3, voffA);
;             PG8_WAIT_V(8); PG8_WAIT_L(0); PG8_BAR; PG8_MMA(1, 0, At, B0); PG8_MMA(1, 1, At, B1); PG8_BAR; PG8_SCHED;
;     ...
;         if constexpr (ALIGN_EPI) { if (wr == 0) PG8_BAR; }
	s_add_i32 s18, s38, s20
	v_lshl_add_u64 v[222:223], v[222:223], 0, s[46:47]
	s_mov_b32 m0, s18
	ds_read_b128 v[176:179], v143 offset:49152
	ds_read_b128 v[180:183], v143 offset:50176
	ds_read_b128 v[184:187], v143 offset:51200
	ds_read_b128 v[188:191], v143 offset:52224
	ds_read_b128 v[206:209], v143 offset:53248
	ds_read_b128 v[210:213], v143 offset:54272
	ds_read_b128 v[214:217], v143 offset:55296
	ds_read_b128 v[218:221], v143 offset:56320
	global_load_lds_dwordx4 v[222:223], off
	s_add_i32 m0, s18, 0x2000
	s_add_u32 s16, s16, 0x80080
	v_lshl_add_u64 v[222:223], v[224:225], 0, s[46:47]
	s_addc_u32 s17, s17, 0
	s_add_i32 s18, s39, s20
	global_load_lds_dwordx4 v[222:223], off
	v_lshl_add_u64 v[222:223], s[16:17], 0, v[132:133]
	s_mov_b32 m0, s18
	s_nop 0
	global_load_lds_dwordx4 v[222:223], off
	v_lshl_add_u64 v[222:223], s[16:17], 0, v[128:129]
	s_add_i32 m0, s18, 0x2000
	s_nop 0
	global_load_lds_dwordx4 v[222:223], off
	v_lshl_add_u64 v[222:223], v[226:227], 0, s[46:47]
	s_mov_b32 m0, s25
	s_nop 0
	global_load_lds_dwordx4 v[222:223], off
	v_lshl_add_u64 v[222:223], v[228:229], 0, s[46:47]
	s_mov_b32 m0, s26
	s_nop 0
	global_load_lds_dwordx4 v[222:223], off
	s_waitcnt vmcnt(8)
	s_waitcnt lgkmcnt(0)
	s_barrier
	s_waitcnt lgkmcnt(0)
	v_mfma_f32_16x16x32_bf16 v[60:63], v[144:147], v[176:179], v[60:63]
	v_mfma_f32_16x16x32_bf16 v[56:59], v[152:155], v[176:179], v[56:59]
	v_mfma_f32_16x16x32_bf16 v[52:55], v[144:147], v[184:187], v[52:55]
	v_mfma_f32_16x16x32_bf16 v[44:47], v[152:155], v[184:187], v[44:47]
	v_mfma_f32_16x16x32_bf16 v[36:39], v[144:147], v[206:209], v[36:39]
	v_mfma_f32_16x16x32_bf16 v[28:31], v[152:155], v[206:209], v[28:31]
	v_mfma_f32_16x16x32_bf16 v[20:23], v[144:147], v[214:217], v[20:23]
	v_mfma_f32_16x16x32_bf16 v[12:15], v[152:155], v[214:217], v[12:15]
	v_mfma_f32_16x16x32_bf16 v[60:63], v[148:151], v[180:183], v[60:63]
	v_mfma_f32_16x16x32_bf16 v[56:59], v[156:159], v[180:183], v[56:59]
	v_mfma_f32_16x16x32_bf16 v[52:55], v[148:151], v[188:191], v[52:55]
	v_mfma_f32_16x16x32_bf16 v[44:47], v[156:159], v[188:191], v[44:47]
	v_mfma_f32_16x16x32_bf16 v[36:39], v[148:151], v[210:213], v[36:39]
	v_mfma_f32_16x16x32_bf16 v[28:31], v[156:159], v[210:213], v[28:31]
	v_mfma_f32_16x16x32_bf16 v[20:23], v[148:151], v[218:221], v[20:23]
	v_mfma_f32_16x16x32_bf16 v[12:15], v[156:159], v[218:221], v[12:15]
	v_mfma_f32_16x16x32_bf16 v[48:51], v[160:163], v[176:179], v[48:51]
	v_mfma_f32_16x16x32_bf16 v[40:43], v[168:171], v[176:179], v[40:43]
	v_mfma_f32_16x16x32_bf16 v[32:35], v[160:163], v[184:187], v[32:35]
	v_mfma_f32_16x16x32_bf16 v[24:27], v[168:171], v[184:187], v[24:27]
	v_mfma_f32_16x16x32_bf16 v[16:19], v[160:163], v[206:209], v[16:19]
	v_mfma_f32_16x16x32_bf16 v[8:11], v[168:171], v[206:209], v[8:11]
	v_mfma_f32_16x16x32_bf16 v[4:7], v[160:163], v[214:217], v[4:7]
	v_mfma_f32_16x16x32_bf16 v[0:3], v[168:171], v[214:217], v[0:3]
	v_mfma_f32_16x16x32_bf16 v[48:51], v[164:167], v[180:183], v[48:51]
	v_mfma_f32_16x16x32_bf16 v[40:43], v[172:175], v[180:183], v[40:43]
	v_mfma_f32_16x16x32_bf16 v[32:35], v[164:167], v[188:191], v[32:35]
	v_mfma_f32_16x16x32_bf16 v[24:27], v[172:175], v[188:191], v[24:27]
	v_mfma_f32_16x16x32_bf16 v[16:19], v[164:167], v[210:213], v[16:19]
	v_mfma_f32_16x16x32_bf16 v[8:11], v[172:175], v[210:213], v[8:11]
	v_mfma_f32_16x16x32_bf16 v[4:7], v[164:167], v[218:221], v[4:7]
	v_mfma_f32_16x16x32_bf16 v[0:3], v[172:175], v[218:221], v[0:3]
	s_add_i32 s37, s37, 2
	s_add_u32 s14, s14, 0x100
	s_addc_u32 s15, s15, 0
	s_add_u32 s35, s35, 0x100
	s_addc_u32 s36, s36, 0
	s_cmp_gt_u32 s37, 29
	s_barrier
	s_cbranch_scc0 .LBB0_130
	s_and_b64 vcc, exec, s[4:5]
	s_cbranch_vccz .LBB0_133
	s_barrier

; #define PG8_STAGE(bufoff, gbase, voff) do { _Pragma("unroll") for (int _i = 0; _i < 2; ++_i) \
;         __builtin_amdgcn_global_load_lds((const unsigned*)((const char*)(gbase) + (voff)[_i]), (LAS unsigned*)(lds + (bufoff) + ldsw + _i * 8192), 16, 0, 0); } while (0)
; #define PG8_LDA(dst, b, h) do { _Pragma("unroll") for (int m = 0; m < 4; ++m) _Pragma("unroll") for (int k = 0; k < 2; ++k) dst[m][k] = *(const LAS bf16x8*)(lds + PG8_SA(b, h) + aoff + m * 2048 + k * 1024); } while (0)
; #define PG8_LDB(dst, b, h) do { _Pragma("unroll") for (int n = 0; n < 2; ++n) _Pragma("unroll") for (int k = 0; k < 2; ++k) dst[n][k] = *(const LAS bf16x8*)(lds + PG8_SB(b, h) + boff + n * 2048 + k * 1024); } while (0)
; #define PG8_WAIT_V(n) asm volatile("s_waitcnt vmcnt(" #n ")" ::: "memory")
; #define PG8_WAIT_L(n) asm volatile("s_waitcnt lgkmcnt(" #n ")" ::: "memory")
; #define PG8_BAR __builtin_amdgcn_s_barrier()
; #define PG8_SCHED __builtin_amdgcn_sched_barrier(0)
; template <class Epi, bool PERMA = false, bool DUAL = false, bool ALIGN_EPI = true, bool SP2 = true>
; __device__ __forceinline__ void gemm_phase(LAS unsigned char* lds, const Gemm g, const StaticOrder& S, const Epi& E) {
;     ...
;         const int nw_ = DUAL ? ((ui + 1) & 1) : 0;
;         const bool has_next = DUAL ? S.next((ui + 1) >> 1, nxt) : S.next(ui + 1, nxt);
;         const bf16_t* gA_ = (DUAL && nw_) ? g.A2 : g.A; const bf16_t* gB_ = (DUAL && nw_) ? g.Bt2 : g.Bt;
;         const char* nA = has_next ? (const char*)gA_ + (size_t)nxt.pm * tstepA : cA; const char* nB = has_next ? (const char*)gB_ + (size_t)nxt.pn * tstepB : cB;
;         for (int t = 0; t < nt; t += 2) {
;             const bool last = (t == nt - 2);
;             const char* a1 = cA + (size_t)(t + 1) * kstep;
;             const char* a2 = last ? nA : cA + (size_t)(t + 2) * kstep; const char* b2 = last ? nB : cB + (size_t)(t + 2) * kstep;
;             const char* a3 = a2 + kstep; const char* b3 = b2 + kstep;
;             if constexpr (SP2) {
;             PG8_LDB(B0, 0, 0); PG8_LDB(B1, 0, 1); PG8_SCHED; PG8_LDA(At, 0, 0); PG8_STAGE(PG8_SA(1, 1), a1 + hstepA, voffA);
;             PG8_WAIT_V(8); PG8_WAIT_L(0); PG8_BAR; PG8_MMA(0, 0, At, B0); PG8_MMA(0, 1, At, B1); PG8_BAR; PG8_SCHED;
;             PG8_LDA(At, 0, 1); PG8_STAGE(PG8_SB(0, 0), b2, voffB); PG8_STAGE(PG8_SB(0, 1), b2 + hstepB, voffB); PG8_STAGE(PG8_SA(0, 0), a2, voffA);
.LBB0_329:
	s_add_u32 s0, s12, 0x100
	s_addc_u32 s1, s13, 0
	s_add_i32 s38, 0, 0x10000
	s_cmp_eq_u32 s37, 4
	s_cselect_b32 s17, s9, s1
	s_cselect_b32 s16, s8, s0
	s_cselect_b32 s15, s7, s36
	s_cselect_b32 s14, s34, s35
	s_add_i32 s39, 0, 0x14000
	v_add_u32_e32 v140, s38, v193
	v_add_u32_e32 v156, s39, v193
	ds_read_b128 v[128:131], v140
	ds_read_b128 v[132:135], v140 offset:1024
	ds_read_b128 v[136:139], v140 offset:2048
	ds_read_b128 v[140:143], v140 offset:3072
	ds_read_b128 v[144:147], v156
	ds_read_b128 v[148:151], v156 offset:1024
	ds_read_b128 v[152:155], v156 offset:2048
	ds_read_b128 v[156:159], v156 offset:3072
	v_lshl_add_u64 v[220:221], s[12:13], 0, v[216:217]
	s_add_i32 m0, s19, 0xc000
	ds_read_b128 v[160:163], v238
	ds_read_b128 v[164:167], v238 offset:1024
	ds_read_b128 v[168:171], v238 offset:2048
	ds_read_b128 v[172:175], v238 offset:3072
	ds_read_b128 v[176:179], v238 offset:4096
	ds_read_b128 v[180:183], v238 offset:5120
	ds_read_b128 v[184:187], v238 offset:6144
	ds_read_b128 v[188:191], v238 offset:7168
	global_load_lds_dwordx4 v[220:221], off
	v_lshl_add_u64 v[220:221], s[12:13], 0, v[218:219]
	s_add_i32 m0, s19, 0xe000
	s_nop 0
	global_load_lds_dwordx4 v[220:221], off
	s_waitcnt vmcnt(8)
	s_waitcnt lgkmcnt(0)
	s_barrier
	s_waitcnt lgkmcnt(0)
	v_mfma_f32_16x16x32_bf16 v[124:127], v[128:131], v[160:163], v[124:127]
	v_mfma_f32_16x16x32_bf16 v[120:123], v[136:139], v[160:163], v[120:123]
	v_mfma_f32_16x16x32_bf16 v[108:111], v[128:131], v[168:171], v[108:111]
	v_mfma_f32_16x16x32_bf16 v[104:107], v[136:139], v[168:171], v[104:107]
	v_mfma_f32_16x16x32_bf16 v[92:95], v[128:131], v[176:179], v[92:95]
	v_mfma_f32_16x16x32_bf16 v[88:91], v[136:139], v[176:179], v[88:91]
	v_mfma_f32_16x16x32_bf16 v[76:79], v[128:131], v[184:187], v[76:79]
	v_mfma_f32_16x16x32_bf16 v[72:75], v[136:139], v[184:187], v[72:75]
	v_mfma_f32_16x16x32_bf16 v[124:127], v[132:135], v[164:167], v[124:127]
	v_mfma_f32_16x16x32_bf16 v[120:123], v[140:143], v[164:167], v[120:123]
	v_mfma_f32_16x16x32_bf16 v[108:111], v[132:135], v[172:175], v[108:111]
	v_mfma_f32_16x16x32_bf16 v[104:107], v[140:143], v[172:175], v[104:107]
	v_mfma_f32_16x16x32_bf16 v[92:95], v[132:135], v[180:183], v[92:95]
	v_mfma_f32_16x16x32_bf16 v[88:91], v[140:143], v[180:183], v[88:91]
	v_mfma_f32_16x16x32_bf16 v[76:79], v[132:135], v[188:191], v[76:79]
	v_mfma_f32_16x16x32_bf16 v[72:75], v[140:143], v[188:191], v[72:75]
	v_mfma_f32_16x16x32_bf16 v[116:119], v[144:147], v[160:163], v[116:119]
	v_mfma_f32_16x16x32_bf16 v[112:115], v[152:155], v[160:163], v[112:115]
	v_mfma_f32_16x16x32_bf16 v[100:103], v[144:147], v[168:171], v[100:103]
	v_mfma_f32_16x16x32_bf16 v[96:99], v[152:155], v[168:171], v[96:99]
	v_mfma_f32_16x16x32_bf16 v[84:87], v[144:147], v[176:179], v[84:87]
	v_mfma_f32_16x16x32_bf16 v[80:83], v[152:155], v[176:179], v[80:83]
	v_mfma_f32_16x16x32_bf16 v[68:71], v[144:147], v[184:187], v[68:71]
	v_mfma_f32_16x16x32_bf16 v[64:67], v[152:155], v[184:187], v[64:67]
	v_mfma_f32_16x16x32_bf16 v[116:119], v[148:151], v[164:167], v[116:119]
	v_mfma_f32_16x16x32_bf16 v[112:115], v[156:159], v[164:167], v[112:115]
	v_mfma_f32_16x16x32_bf16 v[100:103], v[148:151], v[172:175], v[100:103]
	v_mfma_f32_16x16x32_bf16 v[96:99], v[156:159], v[172:175], v[96:99]
	v_mfma_f32_16x16x32_bf16 v[84:87], v[148:151], v[180:183], v[84:87]
	v_mfma_f32_16x16x32_bf16 v[80:83], v[156:159], v[180:183], v[80:83]
	v_mfma_f32_16x16x32_bf16 v[68:71], v[148:151], v[188:191], v[68:71]
	v_mfma_f32_16x16x32_bf16 v[64:67], v[156:159], v[188:191], v[64:67]
	s_barrier
	s_add_i32 s12, s38, s18
	v_lshl_add_u64 v[220:221], s[14:15], 0, v[210:211]
	s_mov_b32 m0, s12
	ds_read_b128 v[160:163], v238 offset:16384
	ds_read_b128 v[164:167], v238 offset:17408
	ds_read_b128 v[168:171], v238 offset:18432
	ds_read_b128 v[172:175], v238 offset:19456
	ds_read_b128 v[176:179], v238 offset:20480
	ds_read_b128 v[180:183], v238 offset:21504
	ds_read_b128 v[184:187], v238 offset:22528
	ds_read_b128 v[188:191], v238 offset:23552
	global_load_lds_dwordx4 v[220:221], off
	s_add_i32 m0, s12, 0x2000
	s_add_u32 s12, s14, 0x20000
	v_lshl_add_u64 v[222:223], s[14:15], 0, v[206:207]
	s_addc_u32 s13, s15, 0
	s_add_i32 s38, s39, s18
	global_load_lds_dwordx4 v[222:223], off
	v_lshl_add_u64 v[224:225], s[12:13], 0, v[210:211]
	s_mov_b32 m0, s38
	v_lshl_add_u64 v[226:227], s[16:17], 0, v[208:209]
	global_load_lds_dwordx4 v[224:225], off
	v_lshl_add_u64 v[224:225], s[12:13], 0, v[206:207]
	s_add_i32 m0, s38, 0x2000
	s_nop 0
	global_load_lds_dwordx4 v[224:225], off
	v_lshl_add_u64 v[224:225], s[16:17], 0, v[212:213]
	s_mov_b32 m0, s19
	s_nop 0
	global_load_lds_dwordx4 v[224:225], off
	s_mov_b32 m0, s20
	s_nop 0
	global_load_lds_dwordx4 v[226:227], off
	s_waitcnt vmcnt(8)
	s_waitcnt lgkmcnt(0)
	s_barrier
; #define PG8_STAGE(bufoff, gbase, voff) do { _Pragma("unroll") for (int _i = 0; _i < 2; ++_i) \
;         __builtin_amdgcn_global_load_lds((const unsigned*)((const char*)(gbase) + (voff)[_i]), (LAS unsigned*)(lds + (bufoff) + ldsw + _i * 8192), 16, 0, 0); } while (0)
; #define PG8_LDA(dst, b, h) do { _Pragma("unroll") for (int m = 0; m < 4; ++m) _Pragma("unroll") for (int k = 0; k < 2; ++k) dst[m][k] = *(const LAS bf16x8*)(lds + PG8_SA(b, h) + aoff + m * 2048 + k * 1024); } while (0)
; #define PG8_LDB(dst, b, h) do { _Pragma("unroll") for (int n = 0; n < 2; ++n) _Pragma("unroll") for (int k = 0; k < 2; ++k) dst[n][k] = *(const LAS bf16x8*)(lds + PG8_SB(b, h) + boff + n * 2048 + k * 1024); } while (0)
; #define PG8_MMA(ai, bj, At, Bt) do { __builtin_amdgcn_s_setprio(1); _Pragma("unroll") for (int m = 0; m < 4; ++m) _Pragma("unroll") for (int n = 0; n < 2; ++n) _Pragma("unroll") for (int k = 0; k < 2; ++k) \
;         acc[ai][bj][m][n] = __builtin_amdgcn_mfma_f32_16x16x32_bf16(Bt[n][k], At[m][k], acc[ai][bj][m][n], 0, 0, 0); __builtin_amdgcn_s_setprio(0); } while (0)
; #define PG8_WAIT_V(n) asm volatile("s_waitcnt vmcnt(" #n ")" ::: "memory")
; #define PG8_WAIT_L(n) asm volatile("s_waitcnt lgkmcnt(" #n ")" ::: "memory")
; #define PG8_BAR __builtin_amdgcn_s_barrier()
; #define PG8_SCHED __builtin_amdgcn_sched_barrier(0)
; template <class Epi, bool PERMA = false, bool DUAL = false, bool ALIGN_EPI = true, bool SP2 = true>
; __device__ __forceinline__ void gemm_phase(LAS unsigned char* lds, const Gemm g, const StaticOrder& S, const Epi& E) {
;     ...
;             PG8_WAIT_V(8); PG8_WAIT_L(0); PG8_BAR; PG8_MMA(1, 0, At, B0); PG8_MMA(1, 1, At, B1); PG8_BAR; PG8_SCHED;
;             PG8_LDB(B0, 1, 0); PG8_LDB(B1, 1, 1); PG8_SCHED; PG8_LDA(At, 1, 0); PG8_STAGE(PG8_SA(0, 1), a2 + hstepA, voffA);
;             PG8_WAIT_V(8); PG8_WAIT_L(0); PG8_BAR; PG8_MMA(0, 0, At, B0); PG8_MMA(0, 1, At, B1); PG8_BAR; PG8_SCHED;
	s_waitcnt lgkmcnt(0)
	v_mfma_f32_16x16x32_bf16 v[60:63], v[128:131], v[160:163], v[60:63]
	v_mfma_f32_16x16x32_bf16 v[56:59], v[136:139], v[160:163], v[56:59]
	v_mfma_f32_16x16x32_bf16 v[44:47], v[128:131], v[168:171], v[44:47]
	v_mfma_f32_16x16x32_bf16 v[40:43], v[136:139], v[168:171], v[40:43]
	v_mfma_f32_16x16x32_bf16 v[28:31], v[128:131], v[176:179], v[28:31]
	v_mfma_f32_16x16x32_bf16 v[24:27], v[136:139], v[176:179], v[24:27]
	v_mfma_f32_16x16x32_bf16 v[12:15], v[128:131], v[184:187], v[12:15]
	v_mfma_f32_16x16x32_bf16 v[8:11], v[136:139], v[184:187], v[8:11]
	v_mfma_f32_16x16x32_bf16 v[60:63], v[132:135], v[164:167], v[60:63]
	v_mfma_f32_16x16x32_bf16 v[56:59], v[140:143], v[164:167], v[56:59]
	v_mfma_f32_16x16x32_bf16 v[44:47], v[132:135], v[172:175], v[44:47]
	v_mfma_f32_16x16x32_bf16 v[40:43], v[140:143], v[172:175], v[40:43]
	v_mfma_f32_16x16x32_bf16 v[28:31], v[132:135], v[180:183], v[28:31]
	v_mfma_f32_16x16x32_bf16 v[24:27], v[140:143], v[180:183], v[24:27]
	v_mfma_f32_16x16x32_bf16 v[12:15], v[132:135], v[188:191], v[12:15]
	v_mfma_f32_16x16x32_bf16 v[8:11], v[140:143], v[188:191], v[8:11]
	v_mfma_f32_16x16x32_bf16 v[52:55], v[144:147], v[160:163], v[52:55]
	v_mfma_f32_16x16x32_bf16 v[48:51], v[152:155], v[160:163], v[48:51]
	v_mfma_f32_16x16x32_bf16 v[36:39], v[144:147], v[168:171], v[36:39]
	v_mfma_f32_16x16x32_bf16 v[32:35], v[152:155], v[168:171], v[32:35]
	v_mfma_f32_16x16x32_bf16 v[20:23], v[144:147], v[176:179], v[20:23]
	v_mfma_f32_16x16x32_bf16 v[16:19], v[152:155], v[176:179], v[16:19]
	v_mfma_f32_16x16x32_bf16 v[4:7], v[144:147], v[184:187], v[4:7]
	v_mfma_f32_16x16x32_bf16 v[0:3], v[152:155], v[184:187], v[0:3]
	v_mfma_f32_16x16x32_bf16 v[52:55], v[148:151], v[164:167], v[52:55]
	v_mfma_f32_16x16x32_bf16 v[48:51], v[156:159], v[164:167], v[48:51]
	v_mfma_f32_16x16x32_bf16 v[36:39], v[148:151], v[172:175], v[36:39]
	v_mfma_f32_16x16x32_bf16 v[32:35], v[156:159], v[172:175], v[32:35]
	v_mfma_f32_16x16x32_bf16 v[20:23], v[148:151], v[180:183], v[20:23]
	v_mfma_f32_16x16x32_bf16 v[16:19], v[156:159], v[180:183], v[16:19]
	v_mfma_f32_16x16x32_bf16 v[4:7], v[148:151], v[188:191], v[4:7]
	v_mfma_f32_16x16x32_bf16 v[0:3], v[156:159], v[188:191], v[0:3]
	s_barrier
	s_add_i32 s38, 0, 0x18000
	s_add_i32 s39, 0, 0x1c000
	v_add_u32_e32 v140, s38, v193
	v_add_u32_e32 v156, s39, v193
	ds_read_b128 v[128:131], v140
	ds_read_b128 v[132:135], v140 offset:1024
	ds_read_b128 v[136:139], v140 offset:2048
	ds_read_b128 v[140:143], v140 offset:3072
	ds_read_b128 v[144:147], v156
	ds_read_b128 v[148:151], v156 offset:1024
	ds_read_b128 v[152:155], v156 offset:2048
	ds_read_b128 v[156:159], v156 offset:3072
	s_add_u32 s12, s16, 0x180000
	s_addc_u32 s13, s17, 0
	s_mov_b32 m0, s21
	v_lshl_add_u64 v[228:229], s[12:13], 0, v[212:213]
	ds_read_b128 v[160:163], v238 offset:32768
	ds_read_b128 v[164:167], v238 offset:33792
	ds_read_b128 v[168:171], v238 offset:34816
	ds_read_b128 v[172:175], v238 offset:35840
	ds_read_b128 v[176:179], v238 offset:36864
	ds_read_b128 v[180:183], v238 offset:37888
	ds_read_b128 v[184:187], v238 offset:38912
	ds_read_b128 v[188:191], v238 offset:39936
	global_load_lds_dwordx4 v[228:229], off
	v_lshl_add_u64 v[228:229], s[12:13], 0, v[208:209]
	s_mov_b32 m0, s22
	s_nop 0
	global_load_lds_dwordx4 v[228:229], off
	s_waitcnt vmcnt(8)
	s_waitcnt lgkmcnt(0)
	s_barrier
	s_waitcnt lgkmcnt(0)
	v_mfma_f32_16x16x32_bf16 v[124:127], v[128:131], v[160:163], v[124:127]
	v_mfma_f32_16x16x32_bf16 v[120:123], v[136:139], v[160:163], v[120:123]
	v_mfma_f32_16x16x32_bf16 v[108:111], v[128:131], v[168:171], v[108:111]
	v_mfma_f32_16x16x32_bf16 v[104:107], v[136:139], v[168:171], v[104:107]
	v_mfma_f32_16x16x32_bf16 v[92:95], v[128:131], v[176:179], v[92:95]
	v_mfma_f32_16x16x32_bf16 v[88:91], v[136:139], v[176:179], v[88:91]
	v_mfma_f32_16x16x32_bf16 v[76:79], v[128:131], v[184:187], v[76:79]
	v_mfma_f32_16x16x32_bf16 v[72:75], v[136:139], v[184:187], v[72:75]
	v_mfma_f32_16x16x32_bf16 v[124:127], v[132:135], v[164:167], v[124:127]
	v_mfma_f32_16x16x32_bf16 v[120:123], v[140:143], v[164:167], v[120:123]
	v_mfma_f32_16x16x32_bf16 v[108:111], v[132:135], v[172:175], v[108:111]
	v_mfma_f32_16x16x32_bf16 v[104:107], v[140:143], v[172:175], v[104:107]
	v_mfma_f32_16x16x32_bf16 v[92:95], v[132:135], v[180:183], v[92:95]
	v_mfma_f32_16x16x32_bf16 v[88:91], v[140:143], v[180:183], v[88:91]
	v_mfma_f32_16x16x32_bf16 v[76:79], v[132:135], v[188:191], v[76:79]
	v_mfma_f32_16x16x32_bf16 v[72:75], v[140:143], v[188:191], v[72:75]
	v_mfma_f32_16x16x32_bf16 v[116:119], v[144:147], v[160:163], v[116:119]
	v_mfma_f32_16x16x32_bf16 v[112:115], v[152:155], v[160:163], v[112:115]
	v_mfma_f32_16x16x32_bf16 v[100:103], v[144:147], v[168:171], v[100:103]
	v_mfma_f32_16x16x32_bf16 v[96:99], v[152:155], v[168:171], v[96:99]
	v_mfma_f32_16x16x32_bf16 v[84:87], v[144:147], v[176:179], v[84:87]
	v_mfma_f32_16x16x32_bf16 v[80:83], v[152:155], v[176:179], v[80:83]
	v_mfma_f32_16x16x32_bf16 v[68:71], v[144:147], v[184:187], v[68:71]
	v_mfma_f32_16x16x32_bf16 v[64:67], v[152:155], v[184:187], v[64:67]
	v_mfma_f32_16x16x32_bf16 v[116:119], v[148:151], v[164:167], v[116:119]
	v_mfma_f32_16x16x32_bf16 v[112:115], v[156:159], v[164:167], v[112:115]
	v_mfma_f32_16x16x32_bf16 v[100:103], v[148:151], v[172:175], v[100:103]
	v_mfma_f32_16x16x32_bf16 v[96:99], v[156:159], v[172:175], v[96:99]
	v_mfma_f32_16x16x32_bf16 v[84:87], v[148:151], v[180:183], v[84:87]
	v_mfma_f32_16x16x32_bf16 v[80:83], v[156:159], v[180:183], v[80:83]
	v_mfma_f32_16x16x32_bf16 v[68:71], v[148:151], v[188:191], v[68:71]
	v_mfma_f32_16x16x32_bf16 v[64:67], v[156:159], v[188:191], v[64:67]
	s_barrier
; #define PG8_STAGE(bufoff, gbase, voff) do { _Pragma("unroll") for (int _i = 0; _i < 2; ++_i) \
;         __builtin_amdgcn_global_load_lds((const unsigned*)((const char*)(gbase) + (voff)[_i]), (LAS unsigned*)(lds + (bufoff) + ldsw + _i * 8192), 16, 0, 0); } while (0)
; #define PG8_LDA(dst, b, h) do { _Pragma("unroll") for (int m = 0; m < 4; ++m) _Pragma("unroll") for (int k = 0; k < 2; ++k) dst[m][k] = *(const LAS bf16x8*)(lds + PG8_SA(b, h) + aoff + m * 2048 + k * 1024); } while (0)
; #define PG8_MMA(ai, bj, At, Bt) do { __builtin_amdgcn_s_setprio(1); _Pragma("unroll") for (int m = 0; m < 4; ++m) _Pragma("unroll") for (int n = 0; n < 2; ++n) _Pragma("unroll") for (int k = 0; k < 2; ++k) \
;         acc[ai][bj][m][n] = __builtin_amdgcn_mfma_f32_16x16x32_bf16(Bt[n][k], At[m][k], acc[ai][bj][m][n], 0, 0, 0); __builtin_amdgcn_s_setprio(0); } while (0)
; #define PG8_WAIT_V(n) asm volatile("s_waitcnt vmcnt(" #n ")" ::: "memory")
; #define PG8_WAIT_L(n) asm volatile("s_waitcnt lgkmcnt(" #n ")" ::: "memory")
; #define PG8_BAR __builtin_amdgcn_s_barrier()
; #define PG8_SCHED __builtin_amdgcn_sched_barrier(0)
; template <class Epi, bool PERMA = false, bool DUAL = false, bool ALIGN_EPI = true, bool SP2 = true>
; __device__ __forceinline__ void gemm_phase(LAS unsigned char* lds, const Gemm g, const StaticOrder& S, const Epi& E) {
;     ...
;             PG8_LDA(At, 1, 1); PG8_STAGE(PG8_SB(1, 0), b3, voffB); PG8_STAGE(PG8_SB(1, 1), b3 + hstepB, voffB); PG8_STAGE(PG8_SA(1, 0), a3, voffA);
;             PG8_WAIT_V(8); PG8_WAIT_L(0); PG8_BAR; PG8_MMA(1, 0, At, B0); PG8_MMA(1, 1, At, B1); PG8_BAR; PG8_SCHED;
;     ...
;         if constexpr (ALIGN_EPI) { if (wr == 0) PG8_BAR; }
	s_add_i32 s12, s38, s18
	v_lshl_add_u64 v[220:221], v[220:221], 0, s[46:47]
	s_mov_b32 m0, s12
	ds_read_b128 v[160:163], v238 offset:49152
	ds_read_b128 v[164:167], v238 offset:50176
	ds_read_b128 v[168:171], v238 offset:51200
	ds_read_b128 v[172:175], v238 offset:52224
	ds_read_b128 v[176:179], v238 offset:53248
	ds_read_b128 v[180:183], v238 offset:54272
	ds_read_b128 v[184:187], v238 offset:55296
	ds_read_b128 v[188:191], v238 offset:56320
	global_load_lds_dwordx4 v[220:221], off
	s_add_i32 m0, s12, 0x2000
	s_add_u32 s12, s14, 0x20080
	v_lshl_add_u64 v[220:221], v[222:223], 0, s[46:47]
	s_addc_u32 s13, s15, 0
	s_add_i32 s14, s39, s18
	global_load_lds_dwordx4 v[220:221], off
	v_lshl_add_u64 v[220:221], s[12:13], 0, v[210:211]
	s_mov_b32 m0, s14
	s_nop 0
	global_load_lds_dwordx4 v[220:221], off
	v_lshl_add_u64 v[220:221], s[12:13], 0, v[206:207]
	s_add_i32 m0, s14, 0x2000
	s_nop 0
	global_load_lds_dwordx4 v[220:221], off
	v_lshl_add_u64 v[220:221], v[224:225], 0, s[46:47]
	s_mov_b32 m0, s25
	s_nop 0
	global_load_lds_dwordx4 v[220:221], off
	v_lshl_add_u64 v[220:221], v[226:227], 0, s[46:47]
	s_mov_b32 m0, s26
	s_nop 0
	global_load_lds_dwordx4 v[220:221], off
	s_waitcnt vmcnt(8)
	s_waitcnt lgkmcnt(0)
	s_barrier
	s_waitcnt lgkmcnt(0)
	v_mfma_f32_16x16x32_bf16 v[60:63], v[128:131], v[160:163], v[60:63]
	v_mfma_f32_16x16x32_bf16 v[56:59], v[136:139], v[160:163], v[56:59]
	v_mfma_f32_16x16x32_bf16 v[44:47], v[128:131], v[168:171], v[44:47]
	v_mfma_f32_16x16x32_bf16 v[40:43], v[136:139], v[168:171], v[40:43]
	v_mfma_f32_16x16x32_bf16 v[28:31], v[128:131], v[176:179], v[28:31]
	v_mfma_f32_16x16x32_bf16 v[24:27], v[136:139], v[176:179], v[24:27]
	v_mfma_f32_16x16x32_bf16 v[12:15], v[128:131], v[184:187], v[12:15]
	v_mfma_f32_16x16x32_bf16 v[8:11], v[136:139], v[184:187], v[8:11]
	v_mfma_f32_16x16x32_bf16 v[60:63], v[132:135], v[164:167], v[60:63]
	v_mfma_f32_16x16x32_bf16 v[56:59], v[140:143], v[164:167], v[56:59]
	v_mfma_f32_16x16x32_bf16 v[44:47], v[132:135], v[172:175], v[44:47]
	v_mfma_f32_16x16x32_bf16 v[40:43], v[140:143], v[172:175], v[40:43]
	v_mfma_f32_16x16x32_bf16 v[28:31], v[132:135], v[180:183], v[28:31]
	v_mfma_f32_16x16x32_bf16 v[24:27], v[140:143], v[180:183], v[24:27]
	v_mfma_f32_16x16x32_bf16 v[12:15], v[132:135], v[188:191], v[12:15]
	v_mfma_f32_16x16x32_bf16 v[8:11], v[140:143], v[188:191], v[8:11]
	v_mfma_f32_16x16x32_bf16 v[52:55], v[144:147], v[160:163], v[52:55]
	v_mfma_f32_16x16x32_bf16 v[48:51], v[152:155], v[160:163], v[48:51]
	v_mfma_f32_16x16x32_bf16 v[36:39], v[144:147], v[168:171], v[36:39]
	v_mfma_f32_16x16x32_bf16 v[32:35], v[152:155], v[168:171], v[32:35]
	v_mfma_f32_16x16x32_bf16 v[20:23], v[144:147], v[176:179], v[20:23]
	v_mfma_f32_16x16x32_bf16 v[16:19], v[152:155], v[176:179], v[16:19]
	v_mfma_f32_16x16x32_bf16 v[4:7], v[144:147], v[184:187], v[4:7]
	v_mfma_f32_16x16x32_bf16 v[0:3], v[152:155], v[184:187], v[0:3]
	v_mfma_f32_16x16x32_bf16 v[52:55], v[148:151], v[164:167], v[52:55]
	v_mfma_f32_16x16x32_bf16 v[48:51], v[156:159], v[164:167], v[48:51]
	v_mfma_f32_16x16x32_bf16 v[36:39], v[148:151], v[172:175], v[36:39]
	v_mfma_f32_16x16x32_bf16 v[32:35], v[156:159], v[172:175], v[32:35]
	v_mfma_f32_16x16x32_bf16 v[20:23], v[148:151], v[180:183], v[20:23]
	v_mfma_f32_16x16x32_bf16 v[16:19], v[156:159], v[180:183], v[16:19]
	v_mfma_f32_16x16x32_bf16 v[4:7], v[148:151], v[188:191], v[4:7]
	v_mfma_f32_16x16x32_bf16 v[0:3], v[156:159], v[188:191], v[0:3]
	s_add_i32 s37, s37, 2
	s_add_u32 s35, s35, 0x100
	s_addc_u32 s36, s36, 0
	s_cmp_gt_u32 s37, 5
	s_mov_b64 s[12:13], s[0:1]
	s_barrier
	s_cbranch_scc0 .LBB0_329
	s_and_b64 vcc, exec, s[4:5]
	s_cbranch_vccz .LBB0_332
	s_barrier

; #define PG8_STAGE(bufoff, gbase, voff) do { _Pragma("unroll") for (int _i = 0; _i < 2; ++_i) \
;         __builtin_amdgcn_global_load_lds((const unsigned*)((const char*)(gbase) + (voff)[_i]), (LAS unsigned*)(lds + (bufoff) + ldsw + _i * 8192), 16, 0, 0); } while (0)
; #define PG8_LDA(dst, b, h) do { _Pragma("unroll") for (int m = 0; m < 4; ++m) _Pragma("unroll") for (int k = 0; k < 2; ++k) dst[m][k] = *(const LAS bf16x8*)(lds + PG8_SA(b, h) + aoff + m * 2048 + k * 1024); } while (0)
; #define PG8_LDB(dst, b, h) do { _Pragma("unroll") for (int n = 0; n < 2; ++n) _Pragma("unroll") for (int k = 0; k < 2; ++k) dst[n][k] = *(const LAS bf16x8*)(lds + PG8_SB(b, h) + boff + n * 2048 + k * 1024); } while (0)
; #define PG8_MMA(ai, bj, At, Bt) do { __builtin_amdgcn_s_setprio(1); _Pragma("unroll") for (int m = 0; m < 4; ++m) _Pragma("unroll") for (int n = 0; n < 2; ++n) _Pragma("unroll") for (int k = 0; k < 2; ++k) \
;         acc[ai][bj][m][n] = __builtin_amdgcn_mfma_f32_16x16x32_bf16(Bt[n][k], At[m][k], acc[ai][bj][m][n], 0, 0, 0); __builtin_amdgcn_s_setprio(0); } while (0)
; #define PG8_WAIT_V(n) asm volatile("s_waitcnt vmcnt(" #n ")" ::: "memory")
; #define PG8_WAIT_L(n) asm volatile("s_waitcnt lgkmcnt(" #n ")" ::: "memory")
; #define PG8_BAR __builtin_amdgcn_s_barrier()
; #define PG8_SCHED __builtin_amdgcn_sched_barrier(0)
; template <class Epi, bool PERMA = false, bool DUAL = false, bool ALIGN_EPI = true, bool SP2 = true>
; __device__ __forceinline__ void gemm_phase(LAS unsigned char* lds, const Gemm g, const StaticOrder& S, const Epi& E) {
;     ...
;             const bool last = (t == nt - 2);
;             const char* a1 = cA + (size_t)(t + 1) * kstep;
;             const char* a2 = last ? nA : cA + (size_t)(t + 2) * kstep; const char* b2 = last ? nB : cB + (size_t)(t + 2) * kstep;
;             const char* a3 = a2 + kstep; const char* b3 = b2 + kstep;
;             if constexpr (SP2) {
;             PG8_LDB(B0, 0, 0); PG8_LDB(B1, 0, 1); PG8_SCHED; PG8_LDA(At, 0, 0); PG8_STAGE(PG8_SA(1, 1), a1 + hstepA, voffA);
;             PG8_WAIT_V(8); PG8_WAIT_L(0); PG8_BAR; PG8_MMA(0, 0, At, B0); PG8_MMA(0, 1, At, B1); PG8_BAR; PG8_SCHED;
;             PG8_LDA(At, 0, 1); PG8_STAGE(PG8_SB(0, 0), b2, voffB); PG8_STAGE(PG8_SB(0, 1), b2 + hstepB, voffB); PG8_STAGE(PG8_SA(0, 0), a2, voffA);
.LBB0_405:
	s_add_u32 s16, s14, 0xfff00080
	s_addc_u32 s17, s15, -1
	s_add_i32 s38, 0, 0x10000
	s_cmp_eq_u32 s37, 28
	s_cselect_b32 s19, s9, s17
	s_cselect_b32 s18, s33, s16
	v_add_u32_e32 v142, s38, v144
	s_cselect_b32 s17, s7, s36
	s_cselect_b32 s16, s34, s35
	s_add_i32 s40, 0, 0x14000
	ds_read_b128 v[146:149], v142
	ds_read_b128 v[150:153], v142 offset:1024
	ds_read_b128 v[154:157], v142 offset:2048
	ds_read_b128 v[158:161], v142 offset:3072
	v_add_u32_e32 v142, s40, v144
	ds_read_b128 v[162:165], v142
	ds_read_b128 v[166:169], v142 offset:1024
	ds_read_b128 v[170:173], v142 offset:2048
	ds_read_b128 v[174:177], v142 offset:3072
	v_lshl_add_u64 v[142:143], s[14:15], 0, v[138:139]
	s_add_i32 m0, s21, 0xc000
	ds_read_b128 v[178:181], v145
	ds_read_b128 v[182:185], v145 offset:1024
	ds_read_b128 v[186:189], v145 offset:2048
	ds_read_b128 v[206:209], v145 offset:3072
	ds_read_b128 v[210:213], v145 offset:4096
	ds_read_b128 v[214:217], v145 offset:5120
	ds_read_b128 v[218:221], v145 offset:6144
	ds_read_b128 v[222:225], v145 offset:7168
	global_load_lds_dwordx4 v[142:143], off
	v_lshl_add_u64 v[142:143], s[14:15], 0, v[140:141]
	s_add_i32 m0, s21, 0xe000
	s_nop 0
	global_load_lds_dwordx4 v[142:143], off
	s_waitcnt vmcnt(8)
	s_waitcnt lgkmcnt(0)
	s_barrier
	s_waitcnt lgkmcnt(0)
	v_mfma_f32_16x16x32_bf16 v[124:127], v[146:149], v[178:181], v[124:127]
	v_mfma_f32_16x16x32_bf16 v[120:123], v[154:157], v[178:181], v[120:123]
	v_mfma_f32_16x16x32_bf16 v[116:119], v[146:149], v[186:189], v[116:119]
	v_mfma_f32_16x16x32_bf16 v[108:111], v[154:157], v[186:189], v[108:111]
	v_mfma_f32_16x16x32_bf16 v[100:103], v[146:149], v[210:213], v[100:103]
	v_mfma_f32_16x16x32_bf16 v[92:95], v[154:157], v[210:213], v[92:95]
	v_mfma_f32_16x16x32_bf16 v[84:87], v[146:149], v[218:221], v[84:87]
	v_mfma_f32_16x16x32_bf16 v[76:79], v[154:157], v[218:221], v[76:79]
	v_mfma_f32_16x16x32_bf16 v[124:127], v[150:153], v[182:185], v[124:127]
	v_mfma_f32_16x16x32_bf16 v[120:123], v[158:161], v[182:185], v[120:123]
	v_mfma_f32_16x16x32_bf16 v[116:119], v[150:153], v[206:209], v[116:119]
	v_mfma_f32_16x16x32_bf16 v[108:111], v[158:161], v[206:209], v[108:111]
	v_mfma_f32_16x16x32_bf16 v[100:103], v[150:153], v[214:217], v[100:103]
	v_mfma_f32_16x16x32_bf16 v[92:95], v[158:161], v[214:217], v[92:95]
	v_mfma_f32_16x16x32_bf16 v[84:87], v[150:153], v[222:225], v[84:87]
	v_mfma_f32_16x16x32_bf16 v[76:79], v[158:161], v[222:225], v[76:79]
	v_mfma_f32_16x16x32_bf16 v[112:115], v[162:165], v[178:181], v[112:115]
	v_mfma_f32_16x16x32_bf16 v[104:107], v[170:173], v[178:181], v[104:107]
	v_mfma_f32_16x16x32_bf16 v[96:99], v[162:165], v[186:189], v[96:99]
	v_mfma_f32_16x16x32_bf16 v[88:91], v[170:173], v[186:189], v[88:91]
	v_mfma_f32_16x16x32_bf16 v[80:83], v[162:165], v[210:213], v[80:83]
	v_mfma_f32_16x16x32_bf16 v[72:75], v[170:173], v[210:213], v[72:75]
	v_mfma_f32_16x16x32_bf16 v[68:71], v[162:165], v[218:221], v[68:71]
	v_mfma_f32_16x16x32_bf16 v[64:67], v[170:173], v[218:221], v[64:67]
	v_mfma_f32_16x16x32_bf16 v[112:115], v[166:169], v[182:185], v[112:115]
	v_mfma_f32_16x16x32_bf16 v[104:107], v[174:177], v[182:185], v[104:107]
	v_mfma_f32_16x16x32_bf16 v[96:99], v[166:169], v[206:209], v[96:99]
	v_mfma_f32_16x16x32_bf16 v[88:91], v[174:177], v[206:209], v[88:91]
	v_mfma_f32_16x16x32_bf16 v[80:83], v[166:169], v[214:217], v[80:83]
	v_mfma_f32_16x16x32_bf16 v[72:75], v[174:177], v[214:217], v[72:75]
	v_mfma_f32_16x16x32_bf16 v[68:71], v[166:169], v[222:225], v[68:71]
	v_mfma_f32_16x16x32_bf16 v[64:67], v[174:177], v[222:225], v[64:67]
	s_barrier
	s_add_i32 s38, s38, s20
	v_lshl_add_u64 v[142:143], s[16:17], 0, v[132:133]
	s_mov_b32 m0, s38
	ds_read_b128 v[178:181], v145 offset:16384
	ds_read_b128 v[182:185], v145 offset:17408
	ds_read_b128 v[186:189], v145 offset:18432
	ds_read_b128 v[206:209], v145 offset:19456
	ds_read_b128 v[210:213], v145 offset:20480
	ds_read_b128 v[214:217], v145 offset:21504
	ds_read_b128 v[218:221], v145 offset:22528
	ds_read_b128 v[222:225], v145 offset:23552
	global_load_lds_dwordx4 v[142:143], off
	s_add_i32 m0, s38, 0x2000
	s_add_u32 s38, s16, 0x80000
	v_lshl_add_u64 v[190:191], s[16:17], 0, v[128:129]
	s_addc_u32 s39, s17, 0
	s_add_i32 s40, s40, s20
	global_load_lds_dwordx4 v[190:191], off
	v_lshl_add_u64 v[226:227], s[38:39], 0, v[132:133]
	s_mov_b32 m0, s40
	v_lshl_add_u64 v[228:229], s[18:19], 0, v[130:131]
	global_load_lds_dwordx4 v[226:227], off
	v_lshl_add_u64 v[226:227], s[38:39], 0, v[128:129]
	s_add_i32 m0, s40, 0x2000
	s_nop 0
	global_load_lds_dwordx4 v[226:227], off
	v_lshl_add_u64 v[226:227], s[18:19], 0, v[134:135]
	s_mov_b32 m0, s21
	s_nop 0
	global_load_lds_dwordx4 v[226:227], off
	s_mov_b32 m0, s22
	s_nop 0
	global_load_lds_dwordx4 v[228:229], off
	s_waitcnt vmcnt(8)
	s_waitcnt lgkmcnt(0)
	s_barrier
; #define PG8_STAGE(bufoff, gbase, voff) do { _Pragma("unroll") for (int _i = 0; _i < 2; ++_i) \
;         __builtin_amdgcn_global_load_lds((const unsigned*)((const char*)(gbase) + (voff)[_i]), (LAS unsigned*)(lds + (bufoff) + ldsw + _i * 8192), 16, 0, 0); } while (0)
; #define PG8_LDA(dst, b, h) do { _Pragma("unroll") for (int m = 0; m < 4; ++m) _Pragma("unroll") for (int k = 0; k < 2; ++k) dst[m][k] = *(const LAS bf16x8*)(lds + PG8_SA(b, h) + aoff + m * 2048 + k * 1024); } while (0)
; #define PG8_LDB(dst, b, h) do { _Pragma("unroll") for (int n = 0; n < 2; ++n) _Pragma("unroll") for (int k = 0; k < 2; ++k) dst[n][k] = *(const LAS bf16x8*)(lds + PG8_SB(b, h) + boff + n * 2048 + k * 1024); } while (0)
; #define PG8_MMA(ai, bj, At, Bt) do { __builtin_amdgcn_s_setprio(1); _Pragma("unroll") for (int m = 0; m < 4; ++m) _Pragma("unroll") for (int n = 0; n < 2; ++n) _Pragma("unroll") for (int k = 0; k < 2; ++k) \
;         acc[ai][bj][m][n] = __builtin_amdgcn_mfma_f32_16x16x32_bf16(Bt[n][k], At[m][k], acc[ai][bj][m][n], 0, 0, 0); __builtin_amdgcn_s_setprio(0); } while (0)
; #define PG8_WAIT_V(n) asm volatile("s_waitcnt vmcnt(" #n ")" ::: "memory")
; #define PG8_WAIT_L(n) asm volatile("s_waitcnt lgkmcnt(" #n ")" ::: "memory")
; #define PG8_BAR __builtin_amdgcn_s_barrier()
; #define PG8_SCHED __builtin_amdgcn_sched_barrier(0)
; template <class Epi, bool PERMA = false, bool DUAL = false, bool ALIGN_EPI = true, bool SP2 = true>
; __device__ __forceinline__ void gemm_phase(LAS unsigned char* lds, const Gemm g, const StaticOrder& S, const Epi& E) {
;     ...
;             PG8_WAIT_V(8); PG8_WAIT_L(0); PG8_BAR; PG8_MMA(1, 0, At, B0); PG8_MMA(1, 1, At, B1); PG8_BAR; PG8_SCHED;
;             PG8_LDB(B0, 1, 0); PG8_LDB(B1, 1, 1); PG8_SCHED; PG8_LDA(At, 1, 0); PG8_STAGE(PG8_SA(0, 1), a2 + hstepA, voffA);
;             PG8_WAIT_V(8); PG8_WAIT_L(0); PG8_BAR; PG8_MMA(0, 0, At, B0); PG8_MMA(0, 1, At, B1); PG8_BAR; PG8_SCHED;
	s_waitcnt lgkmcnt(0)
	v_mfma_f32_16x16x32_bf16 v[60:63], v[146:149], v[178:181], v[60:63]
	v_mfma_f32_16x16x32_bf16 v[56:59], v[154:157], v[178:181], v[56:59]
	v_mfma_f32_16x16x32_bf16 v[52:55], v[146:149], v[186:189], v[52:55]
	v_mfma_f32_16x16x32_bf16 v[44:47], v[154:157], v[186:189], v[44:47]
	v_mfma_f32_16x16x32_bf16 v[36:39], v[146:149], v[210:213], v[36:39]
	v_mfma_f32_16x16x32_bf16 v[28:31], v[154:157], v[210:213], v[28:31]
	v_mfma_f32_16x16x32_bf16 v[20:23], v[146:149], v[218:221], v[20:23]
	v_mfma_f32_16x16x32_bf16 v[12:15], v[154:157], v[218:221], v[12:15]
	v_mfma_f32_16x16x32_bf16 v[60:63], v[150:153], v[182:185], v[60:63]
	v_mfma_f32_16x16x32_bf16 v[56:59], v[158:161], v[182:185], v[56:59]
	v_mfma_f32_16x16x32_bf16 v[52:55], v[150:153], v[206:209], v[52:55]
	v_mfma_f32_16x16x32_bf16 v[44:47], v[158:161], v[206:209], v[44:47]
	v_mfma_f32_16x16x32_bf16 v[36:39], v[150:153], v[214:217], v[36:39]
	v_mfma_f32_16x16x32_bf16 v[28:31], v[158:161], v[214:217], v[28:31]
	v_mfma_f32_16x16x32_bf16 v[20:23], v[150:153], v[222:225], v[20:23]
	v_mfma_f32_16x16x32_bf16 v[12:15], v[158:161], v[222:225], v[12:15]
	v_mfma_f32_16x16x32_bf16 v[48:51], v[162:165], v[178:181], v[48:51]
	v_mfma_f32_16x16x32_bf16 v[40:43], v[170:173], v[178:181], v[40:43]
	v_mfma_f32_16x16x32_bf16 v[32:35], v[162:165], v[186:189], v[32:35]
	v_mfma_f32_16x16x32_bf16 v[24:27], v[170:173], v[186:189], v[24:27]
	v_mfma_f32_16x16x32_bf16 v[16:19], v[162:165], v[210:213], v[16:19]
	v_mfma_f32_16x16x32_bf16 v[8:11], v[170:173], v[210:213], v[8:11]
	v_mfma_f32_16x16x32_bf16 v[4:7], v[162:165], v[218:221], v[4:7]
	v_mfma_f32_16x16x32_bf16 v[0:3], v[170:173], v[218:221], v[0:3]
	v_mfma_f32_16x16x32_bf16 v[48:51], v[166:169], v[182:185], v[48:51]
	v_mfma_f32_16x16x32_bf16 v[40:43], v[174:177], v[182:185], v[40:43]
	v_mfma_f32_16x16x32_bf16 v[32:35], v[166:169], v[206:209], v[32:35]
	v_mfma_f32_16x16x32_bf16 v[24:27], v[174:177], v[206:209], v[24:27]
	v_mfma_f32_16x16x32_bf16 v[16:19], v[166:169], v[214:217], v[16:19]
	v_mfma_f32_16x16x32_bf16 v[8:11], v[174:177], v[214:217], v[8:11]
	v_mfma_f32_16x16x32_bf16 v[4:7], v[166:169], v[222:225], v[4:7]
	v_mfma_f32_16x16x32_bf16 v[0:3], v[174:177], v[222:225], v[0:3]
	s_barrier
	s_add_i32 s38, 0, 0x18000
	s_add_i32 s39, 0, 0x1c000
	v_add_u32_e32 v158, s38, v144
	v_add_u32_e32 v174, s39, v144
	ds_read_b128 v[146:149], v158
	ds_read_b128 v[150:153], v158 offset:1024
	ds_read_b128 v[154:157], v158 offset:2048
	ds_read_b128 v[158:161], v158 offset:3072
	ds_read_b128 v[162:165], v174
	ds_read_b128 v[166:169], v174 offset:1024
	ds_read_b128 v[170:173], v174 offset:2048
	ds_read_b128 v[174:177], v174 offset:3072
	s_add_u32 s18, s18, 0x100000
	s_addc_u32 s19, s19, 0
	s_mov_b32 m0, s23
	v_lshl_add_u64 v[238:239], s[18:19], 0, v[134:135]
	ds_read_b128 v[178:181], v145 offset:32768
	ds_read_b128 v[182:185], v145 offset:33792
	ds_read_b128 v[186:189], v145 offset:34816
	ds_read_b128 v[206:209], v145 offset:35840
	ds_read_b128 v[210:213], v145 offset:36864
	ds_read_b128 v[214:217], v145 offset:37888
	ds_read_b128 v[218:221], v145 offset:38912
	ds_read_b128 v[222:225], v145 offset:39936
	global_load_lds_dwordx4 v[238:239], off
	v_lshl_add_u64 v[238:239], s[18:19], 0, v[130:131]
	s_mov_b32 m0, s24
	s_nop 0
	global_load_lds_dwordx4 v[238:239], off
	s_waitcnt vmcnt(8)
	s_waitcnt lgkmcnt(0)
	s_barrier
	s_waitcnt lgkmcnt(0)
	v_mfma_f32_16x16x32_bf16 v[124:127], v[146:149], v[178:181], v[124:127]
	v_mfma_f32_16x16x32_bf16 v[120:123], v[154:157], v[178:181], v[120:123]
	v_mfma_f32_16x16x32_bf16 v[116:119], v[146:149], v[186:189], v[116:119]
	v_mfma_f32_16x16x32_bf16 v[108:111], v[154:157], v[186:189], v[108:111]
	v_mfma_f32_16x16x32_bf16 v[100:103], v[146:149], v[210:213], v[100:103]
	v_mfma_f32_16x16x32_bf16 v[92:95], v[154:157], v[210:213], v[92:95]
	v_mfma_f32_16x16x32_bf16 v[84:87], v[146:149], v[218:221], v[84:87]
	v_mfma_f32_16x16x32_bf16 v[76:79], v[154:157], v[218:221], v[76:79]
	v_mfma_f32_16x16x32_bf16 v[124:127], v[150:153], v[182:185], v[124:127]
	v_mfma_f32_16x16x32_bf16 v[120:123], v[158:161], v[182:185], v[120:123]
	v_mfma_f32_16x16x32_bf16 v[116:119], v[150:153], v[206:209], v[116:119]
	v_mfma_f32_16x16x32_bf16 v[108:111], v[158:161], v[206:209], v[108:111]
	v_mfma_f32_16x16x32_bf16 v[100:103], v[150:153], v[214:217], v[100:103]
	v_mfma_f32_16x16x32_bf16 v[92:95], v[158:161], v[214:217], v[92:95]
	v_mfma_f32_16x16x32_bf16 v[84:87], v[150:153], v[222:225], v[84:87]
	v_mfma_f32_16x16x32_bf16 v[76:79], v[158:161], v[222:225], v[76:79]
	v_mfma_f32_16x16x32_bf16 v[112:115], v[162:165], v[178:181], v[112:115]
	v_mfma_f32_16x16x32_bf16 v[104:107], v[170:173], v[178:181], v[104:107]
	v_mfma_f32_16x16x32_bf16 v[96:99], v[162:165], v[186:189], v[96:99]
	v_mfma_f32_16x16x32_bf16 v[88:91], v[170:173], v[186:189], v[88:91]
	v_mfma_f32_16x16x32_bf16 v[80:83], v[162:165], v[210:213], v[80:83]
	v_mfma_f32_16x16x32_bf16 v[72:75], v[170:173], v[210:213], v[72:75]
	v_mfma_f32_16x16x32_bf16 v[68:71], v[162:165], v[218:221], v[68:71]
	v_mfma_f32_16x16x32_bf16 v[64:67], v[170:173], v[218:221], v[64:67]
	v_mfma_f32_16x16x32_bf16 v[112:115], v[166:169], v[182:185], v[112:115]
	v_mfma_f32_16x16x32_bf16 v[104:107], v[174:177], v[182:185], v[104:107]
	v_mfma_f32_16x16x32_bf16 v[96:99], v[166:169], v[206:209], v[96:99]
	v_mfma_f32_16x16x32_bf16 v[88:91], v[174:177], v[206:209], v[88:91]
	v_mfma_f32_16x16x32_bf16 v[80:83], v[166:169], v[214:217], v[80:83]
	v_mfma_f32_16x16x32_bf16 v[72:75], v[174:177], v[214:217], v[72:75]
	v_mfma_f32_16x16x32_bf16 v[68:71], v[166:169], v[222:225], v[68:71]
	v_mfma_f32_16x16x32_bf16 v[64:67], v[174:177], v[222:225], v[64:67]
	s_barrier
; #define PG8_STAGE(bufoff, gbase, voff) do { _Pragma("unroll") for (int _i = 0; _i < 2; ++_i) \
;         __builtin_amdgcn_global_load_lds((const unsigned*)((const char*)(gbase) + (voff)[_i]), (LAS unsigned*)(lds + (bufoff) + ldsw + _i * 8192), 16, 0, 0); } while (0)
; #define PG8_LDA(dst, b, h) do { _Pragma("unroll") for (int m = 0; m < 4; ++m) _Pragma("unroll") for (int k = 0; k < 2; ++k) dst[m][k] = *(const LAS bf16x8*)(lds + PG8_SA(b, h) + aoff + m * 2048 + k * 1024); } while (0)
; #define PG8_MMA(ai, bj, At, Bt) do { __builtin_amdgcn_s_setprio(1); _Pragma("unroll") for (int m = 0; m < 4; ++m) _Pragma("unroll") for (int n = 0; n < 2; ++n) _Pragma("unroll") for (int k = 0; k < 2; ++k) \
;         acc[ai][bj][m][n] = __builtin_amdgcn_mfma_f32_16x16x32_bf16(Bt[n][k], At[m][k], acc[ai][bj][m][n], 0, 0, 0); __builtin_amdgcn_s_setprio(0); } while (0)
; #define PG8_WAIT_V(n) asm volatile("s_waitcnt vmcnt(" #n ")" ::: "memory")
; #define PG8_WAIT_L(n) asm volatile("s_waitcnt lgkmcnt(" #n ")" ::: "memory")
; #define PG8_BAR __builtin_amdgcn_s_barrier()
; #define PG8_SCHED __builtin_amdgcn_sched_barrier(0)
; template <class Epi, bool PERMA = false, bool DUAL = false, bool ALIGN_EPI = true, bool SP2 = true>
; __device__ __forceinline__ void gemm_phase(LAS unsigned char* lds, const Gemm g, const StaticOrder& S, const Epi& E) {
;     ...
;             PG8_LDA(At, 1, 1); PG8_STAGE(PG8_SB(1, 0), b3, voffB); PG8_STAGE(PG8_SB(1, 1), b3 + hstepB, voffB); PG8_STAGE(PG8_SA(1, 0), a3, voffA);
;             PG8_WAIT_V(8); PG8_WAIT_L(0); PG8_BAR; PG8_MMA(1, 0, At, B0); PG8_MMA(1, 1, At, B1); PG8_BAR; PG8_SCHED;
;     ...
;         if constexpr (ALIGN_EPI) { if (wr == 0) PG8_BAR; }
	s_add_i32 s18, s38, s20
	v_lshl_add_u64 v[142:143], v[142:143], 0, s[46:47]
	s_mov_b32 m0, s18
	ds_read_b128 v[178:181], v145 offset:49152
	ds_read_b128 v[182:185], v145 offset:50176
	ds_read_b128 v[186:189], v145 offset:51200
	ds_read_b128 v[206:209], v145 offset:52224
	ds_read_b128 v[210:213], v145 offset:53248
	ds_read_b128 v[214:217], v145 offset:54272
	ds_read_b128 v[218:221], v145 offset:55296
	ds_read_b128 v[222:225], v145 offset:56320
	global_load_lds_dwordx4 v[142:143], off
	s_add_i32 m0, s18, 0x2000
	s_add_u32 s16, s16, 0x80080
	v_lshl_add_u64 v[142:143], v[190:191], 0, s[46:47]
	s_addc_u32 s17, s17, 0
	s_add_i32 s18, s39, s20
	global_load_lds_dwordx4 v[142:143], off
	v_lshl_add_u64 v[142:143], s[16:17], 0, v[132:133]
	s_mov_b32 m0, s18
	s_nop 0
	global_load_lds_dwordx4 v[142:143], off
	v_lshl_add_u64 v[142:143], s[16:17], 0, v[128:129]
	s_add_i32 m0, s18, 0x2000
	s_nop 0
	global_load_lds_dwordx4 v[142:143], off
	v_lshl_add_u64 v[142:143], v[226:227], 0, s[46:47]
	s_mov_b32 m0, s27
	s_nop 0
	global_load_lds_dwordx4 v[142:143], off
	v_lshl_add_u64 v[142:143], v[228:229], 0, s[46:47]
	s_mov_b32 m0, s28
	s_nop 0
	global_load_lds_dwordx4 v[142:143], off
	s_waitcnt vmcnt(8)
	s_waitcnt lgkmcnt(0)
	s_barrier
	s_waitcnt lgkmcnt(0)
	v_mfma_f32_16x16x32_bf16 v[60:63], v[146:149], v[178:181], v[60:63]
	v_mfma_f32_16x16x32_bf16 v[56:59], v[154:157], v[178:181], v[56:59]
	v_mfma_f32_16x16x32_bf16 v[52:55], v[146:149], v[186:189], v[52:55]
	v_mfma_f32_16x16x32_bf16 v[44:47], v[154:157], v[186:189], v[44:47]
	v_mfma_f32_16x16x32_bf16 v[36:39], v[146:149], v[210:213], v[36:39]
	v_mfma_f32_16x16x32_bf16 v[28:31], v[154:157], v[210:213], v[28:31]
	v_mfma_f32_16x16x32_bf16 v[20:23], v[146:149], v[218:221], v[20:23]
	v_mfma_f32_16x16x32_bf16 v[12:15], v[154:157], v[218:221], v[12:15]
	v_mfma_f32_16x16x32_bf16 v[60:63], v[150:153], v[182:185], v[60:63]
	v_mfma_f32_16x16x32_bf16 v[56:59], v[158:161], v[182:185], v[56:59]
	v_mfma_f32_16x16x32_bf16 v[52:55], v[150:153], v[206:209], v[52:55]
	v_mfma_f32_16x16x32_bf16 v[44:47], v[158:161], v[206:209], v[44:47]
	v_mfma_f32_16x16x32_bf16 v[36:39], v[150:153], v[214:217], v[36:39]
	v_mfma_f32_16x16x32_bf16 v[28:31], v[158:161], v[214:217], v[28:31]
	v_mfma_f32_16x16x32_bf16 v[20:23], v[150:153], v[222:225], v[20:23]
	v_mfma_f32_16x16x32_bf16 v[12:15], v[158:161], v[222:225], v[12:15]
	v_mfma_f32_16x16x32_bf16 v[48:51], v[162:165], v[178:181], v[48:51]
	v_mfma_f32_16x16x32_bf16 v[40:43], v[170:173], v[178:181], v[40:43]
	v_mfma_f32_16x16x32_bf16 v[32:35], v[162:165], v[186:189], v[32:35]
	v_mfma_f32_16x16x32_bf16 v[24:27], v[170:173], v[186:189], v[24:27]
	v_mfma_f32_16x16x32_bf16 v[16:19], v[162:165], v[210:213], v[16:19]
	v_mfma_f32_16x16x32_bf16 v[8:11], v[170:173], v[210:213], v[8:11]
	v_mfma_f32_16x16x32_bf16 v[4:7], v[162:165], v[218:221], v[4:7]
	v_mfma_f32_16x16x32_bf16 v[0:3], v[170:173], v[218:221], v[0:3]
	v_mfma_f32_16x16x32_bf16 v[48:51], v[166:169], v[182:185], v[48:51]
	v_mfma_f32_16x16x32_bf16 v[40:43], v[174:177], v[182:185], v[40:43]
	v_mfma_f32_16x16x32_bf16 v[32:35], v[166:169], v[206:209], v[32:35]
	v_mfma_f32_16x16x32_bf16 v[24:27], v[174:177], v[206:209], v[24:27]
	v_mfma_f32_16x16x32_bf16 v[16:19], v[166:169], v[214:217], v[16:19]
	v_mfma_f32_16x16x32_bf16 v[8:11], v[174:177], v[214:217], v[8:11]
	v_mfma_f32_16x16x32_bf16 v[4:7], v[166:169], v[222:225], v[4:7]
	v_mfma_f32_16x16x32_bf16 v[0:3], v[174:177], v[222:225], v[0:3]
	s_add_i32 s37, s37, 2
	s_add_u32 s14, s14, 0x100
	s_addc_u32 s15, s15, 0
	s_add_u32 s35, s35, 0x100
	s_addc_u32 s36, s36, 0
	s_cmp_gt_u32 s37, 29
	s_barrier
	s_cbranch_scc0 .LBB0_405
	s_and_b64 vcc, exec, s[4:5]
	s_cbranch_vccz .LBB0_408
	s_barrier

; #define PG8_STAGE(bufoff, gbase, voff) do { _Pragma("unroll") for (int _i = 0; _i < 2; ++_i) \
;         __builtin_amdgcn_global_load_lds((const unsigned*)((const char*)(gbase) + (voff)[_i]), (LAS unsigned*)(lds + (bufoff) + ldsw + _i * 8192), 16, 0, 0); } while (0)
; #define PG8_LDA(dst, b, h) do { _Pragma("unroll") for (int m = 0; m < 4; ++m) _Pragma("unroll") for (int k = 0; k < 2; ++k) dst[m][k] = *(const LAS bf16x8*)(lds + PG8_SA(b, h) + aoff + m * 2048 + k * 1024); } while (0)
; #define PG8_LDB(dst, b, h) do { _Pragma("unroll") for (int n = 0; n < 2; ++n) _Pragma("unroll") for (int k = 0; k < 2; ++k) dst[n][k] = *(const LAS bf16x8*)(lds + PG8_SB(b, h) + boff + n * 2048 + k * 1024); } while (0)
; #define PG8_MMA(ai, bj, At, Bt) do { __builtin_amdgcn_s_setprio(1); _Pragma("unroll") for (int m = 0; m < 4; ++m) _Pragma("unroll") for (int n = 0; n < 2; ++n) _Pragma("unroll") for (int k = 0; k < 2; ++k) \
;         acc[ai][bj][m][n] = __builtin_amdgcn_mfma_f32_16x16x32_bf16(Bt[n][k], At[m][k], acc[ai][bj][m][n], 0, 0, 0); __builtin_amdgcn_s_setprio(0); } while (0)
; #define PG8_WAIT_V(n) asm volatile("s_waitcnt vmcnt(" #n ")" ::: "memory")
; #define PG8_WAIT_L(n) asm volatile("s_waitcnt lgkmcnt(" #n ")" ::: "memory")
; #define PG8_BAR __builtin_amdgcn_s_barrier()
; #define PG8_SCHED __builtin_amdgcn_sched_barrier(0)
; template <class Epi, bool PERMA = false, bool DUAL = false, bool ALIGN_EPI = true, bool SP2 = true>
; __device__ __forceinline__ void gemm_phase(LAS unsigned char* lds, const Gemm g, const StaticOrder& S, const Epi& E) {
;     ...
;             const bool last = (t == nt - 2);
;             const char* a1 = cA + (size_t)(t + 1) * kstep;
;             const char* a2 = last ? nA : cA + (size_t)(t + 2) * kstep; const char* b2 = last ? nB : cB + (size_t)(t + 2) * kstep;
;             const char* a3 = a2 + kstep; const char* b3 = b2 + kstep;
;             if constexpr (SP2) {
;             PG8_LDB(B0, 0, 0); PG8_LDB(B1, 0, 1); PG8_SCHED; PG8_LDA(At, 0, 0); PG8_STAGE(PG8_SA(1, 1), a1 + hstepA, voffA);
;             PG8_WAIT_V(8); PG8_WAIT_L(0); PG8_BAR; PG8_MMA(0, 0, At, B0); PG8_MMA(0, 1, At, B1); PG8_BAR; PG8_SCHED;
;             PG8_LDA(At, 0, 1); PG8_STAGE(PG8_SB(0, 0), b2, voffB); PG8_STAGE(PG8_SB(0, 1), b2 + hstepB, voffB); PG8_STAGE(PG8_SA(0, 0), a2, voffA);
.LBB0_528:
	s_add_u32 s22, s20, 0x100
	s_addc_u32 s23, s21, 0
	s_add_i32 s52, 0, 0x10000
	s_cmp_eq_u32 s51, 28
	s_cselect_b32 s27, s15, s23
	s_cselect_b32 s26, s39, s22
	s_cselect_b32 s25, s13, s50
	s_cselect_b32 s24, s48, s49
	s_add_i32 s53, 0, 0x14000
	v_add_u32_e32 v108, s52, v193
	v_add_u32_e32 v124, s53, v193
	ds_read_b128 v[96:99], v108
	ds_read_b128 v[100:103], v108 offset:1024
	ds_read_b128 v[104:107], v108 offset:2048
	ds_read_b128 v[108:111], v108 offset:3072
	ds_read_b128 v[112:115], v124
	ds_read_b128 v[116:119], v124 offset:1024
	ds_read_b128 v[120:123], v124 offset:2048
	ds_read_b128 v[124:127], v124 offset:3072
	v_lshl_add_u64 v[220:221], s[20:21], 0, v[216:217]
	s_add_i32 m0, s29, 0xc000
	ds_read_b128 v[128:131], v224
	ds_read_b128 v[132:135], v224 offset:1024
	ds_read_b128 v[136:139], v224 offset:2048
	ds_read_b128 v[144:147], v224 offset:3072
	ds_read_b128 v[152:155], v224 offset:4096
	ds_read_b128 v[160:163], v224 offset:5120
	ds_read_b128 v[168:171], v224 offset:6144
	ds_read_b128 v[188:191], v224 offset:7168
	global_load_lds_dwordx4 v[220:221], off
	v_lshl_add_u64 v[220:221], s[20:21], 0, v[218:219]
	s_add_i32 m0, s29, 0xe000
	s_nop 0
	global_load_lds_dwordx4 v[220:221], off
	s_waitcnt vmcnt(8)
	s_waitcnt lgkmcnt(0)
	s_barrier
	s_waitcnt lgkmcnt(0)
	v_mfma_f32_16x16x32_bf16 v[184:187], v[96:99], v[128:131], v[184:187]
	v_mfma_f32_16x16x32_bf16 v[92:95], v[104:107], v[128:131], v[92:95]
	v_mfma_f32_16x16x32_bf16 v[180:183], v[96:99], v[136:139], v[180:183]
	v_mfma_f32_16x16x32_bf16 v[88:91], v[104:107], v[136:139], v[88:91]
	v_mfma_f32_16x16x32_bf16 v[176:179], v[96:99], v[152:155], v[176:179]
	v_mfma_f32_16x16x32_bf16 v[84:87], v[104:107], v[152:155], v[84:87]
	v_mfma_f32_16x16x32_bf16 v[172:175], v[96:99], v[168:171], v[172:175]
	v_mfma_f32_16x16x32_bf16 v[80:83], v[104:107], v[168:171], v[80:83]
	v_mfma_f32_16x16x32_bf16 v[184:187], v[100:103], v[132:135], v[184:187]
	v_mfma_f32_16x16x32_bf16 v[92:95], v[108:111], v[132:135], v[92:95]
	v_mfma_f32_16x16x32_bf16 v[180:183], v[100:103], v[144:147], v[180:183]
	v_mfma_f32_16x16x32_bf16 v[88:91], v[108:111], v[144:147], v[88:91]
	v_mfma_f32_16x16x32_bf16 v[176:179], v[100:103], v[160:163], v[176:179]
	v_mfma_f32_16x16x32_bf16 v[84:87], v[108:111], v[160:163], v[84:87]
	v_mfma_f32_16x16x32_bf16 v[172:175], v[100:103], v[188:191], v[172:175]
	v_mfma_f32_16x16x32_bf16 v[80:83], v[108:111], v[188:191], v[80:83]
	v_mfma_f32_16x16x32_bf16 v[164:167], v[112:115], v[128:131], v[164:167]
	v_mfma_f32_16x16x32_bf16 v[76:79], v[120:123], v[128:131], v[76:79]
	v_mfma_f32_16x16x32_bf16 v[72:75], v[120:123], v[136:139], v[72:75]
	v_mfma_f32_16x16x32_bf16 v[68:71], v[120:123], v[152:155], v[68:71]
	v_mfma_f32_16x16x32_bf16 v[64:67], v[120:123], v[168:171], v[64:67]
	v_mfma_f32_16x16x32_bf16 v[164:167], v[116:119], v[132:135], v[164:167]
	v_mfma_f32_16x16x32_bf16 v[76:79], v[124:127], v[132:135], v[76:79]
	v_mfma_f32_16x16x32_bf16 v[128:131], v[112:115], v[136:139], v[156:159]
	v_mfma_f32_16x16x32_bf16 v[72:75], v[124:127], v[144:147], v[72:75]
	v_mfma_f32_16x16x32_bf16 v[132:135], v[112:115], v[152:155], v[148:151]
	v_mfma_f32_16x16x32_bf16 v[68:71], v[124:127], v[160:163], v[68:71]
	v_mfma_f32_16x16x32_bf16 v[136:139], v[112:115], v[168:171], v[140:143]
	v_mfma_f32_16x16x32_bf16 v[64:67], v[124:127], v[188:191], v[64:67]
	v_mfma_f32_16x16x32_bf16 v[128:131], v[116:119], v[144:147], v[128:131]
	v_mfma_f32_16x16x32_bf16 v[132:135], v[116:119], v[160:163], v[132:135]
	v_mfma_f32_16x16x32_bf16 v[136:139], v[116:119], v[188:191], v[136:139]
	s_barrier
	s_add_i32 s20, s52, s28
	v_lshl_add_u64 v[220:221], s[24:25], 0, v[210:211]
	s_mov_b32 m0, s20
	ds_read_b128 v[140:143], v224 offset:16384
	ds_read_b128 v[144:147], v224 offset:17408
	ds_read_b128 v[148:151], v224 offset:18432
	ds_read_b128 v[152:155], v224 offset:19456
	ds_read_b128 v[156:159], v224 offset:20480
	ds_read_b128 v[160:163], v224 offset:21504
	ds_read_b128 v[168:171], v224 offset:22528
	ds_read_b128 v[188:191], v224 offset:23552
	global_load_lds_dwordx4 v[220:221], off
	s_add_i32 m0, s20, 0x2000
	s_add_u32 s20, s24, 0x80000
	v_lshl_add_u64 v[238:239], s[24:25], 0, v[206:207]
	s_addc_u32 s21, s25, 0
	s_add_i32 s52, s53, s28
	global_load_lds_dwordx4 v[238:239], off
	v_lshl_add_u64 v[226:227], s[20:21], 0, v[210:211]
	s_mov_b32 m0, s52
	v_lshl_add_u64 v[240:241], s[26:27], 0, v[212:213]
	global_load_lds_dwordx4 v[226:227], off
	v_lshl_add_u64 v[226:227], s[20:21], 0, v[206:207]
	s_add_i32 m0, s52, 0x2000
	v_lshl_add_u64 v[242:243], s[26:27], 0, v[208:209]
	global_load_lds_dwordx4 v[226:227], off
	s_mov_b32 m0, s29
	s_nop 0
	global_load_lds_dwordx4 v[240:241], off
	s_mov_b32 m0, s30
	s_nop 0
	global_load_lds_dwordx4 v[242:243], off
	s_waitcnt vmcnt(8)
	s_waitcnt lgkmcnt(0)
	s_barrier
; #define PG8_STAGE(bufoff, gbase, voff) do { _Pragma("unroll") for (int _i = 0; _i < 2; ++_i) \
;         __builtin_amdgcn_global_load_lds((const unsigned*)((const char*)(gbase) + (voff)[_i]), (LAS unsigned*)(lds + (bufoff) + ldsw + _i * 8192), 16, 0, 0); } while (0)
; #define PG8_LDA(dst, b, h) do { _Pragma("unroll") for (int m = 0; m < 4; ++m) _Pragma("unroll") for (int k = 0; k < 2; ++k) dst[m][k] = *(const LAS bf16x8*)(lds + PG8_SA(b, h) + aoff + m * 2048 + k * 1024); } while (0)
; #define PG8_LDB(dst, b, h) do { _Pragma("unroll") for (int n = 0; n < 2; ++n) _Pragma("unroll") for (int k = 0; k < 2; ++k) dst[n][k] = *(const LAS bf16x8*)(lds + PG8_SB(b, h) + boff + n * 2048 + k * 1024); } while (0)
; #define PG8_MMA(ai, bj, At, Bt) do { __builtin_amdgcn_s_setprio(1); _Pragma("unroll") for (int m = 0; m < 4; ++m) _Pragma("unroll") for (int n = 0; n < 2; ++n) _Pragma("unroll") for (int k = 0; k < 2; ++k) \
;         acc[ai][bj][m][n] = __builtin_amdgcn_mfma_f32_16x16x32_bf16(Bt[n][k], At[m][k], acc[ai][bj][m][n], 0, 0, 0); __builtin_amdgcn_s_setprio(0); } while (0)
; #define PG8_WAIT_V(n) asm volatile("s_waitcnt vmcnt(" #n ")" ::: "memory")
; #define PG8_WAIT_L(n) asm volatile("s_waitcnt lgkmcnt(" #n ")" ::: "memory")
; #define PG8_BAR __builtin_amdgcn_s_barrier()
; #define PG8_SCHED __builtin_amdgcn_sched_barrier(0)
; template <class Epi, bool PERMA = false, bool DUAL = false, bool ALIGN_EPI = true, bool SP2 = true>
; __device__ __forceinline__ void gemm_phase(LAS unsigned char* lds, const Gemm g, const StaticOrder& S, const Epi& E) {
;     ...
;             PG8_WAIT_V(8); PG8_WAIT_L(0); PG8_BAR; PG8_MMA(1, 0, At, B0); PG8_MMA(1, 1, At, B1); PG8_BAR; PG8_SCHED;
;             PG8_LDB(B0, 1, 0); PG8_LDB(B1, 1, 1); PG8_SCHED; PG8_LDA(At, 1, 0); PG8_STAGE(PG8_SA(0, 1), a2 + hstepA, voffA);
;             PG8_WAIT_V(8); PG8_WAIT_L(0); PG8_BAR; PG8_MMA(0, 0, At, B0); PG8_MMA(0, 1, At, B1); PG8_BAR; PG8_SCHED;
	s_waitcnt lgkmcnt(0)
	v_mfma_f32_16x16x32_bf16 v[60:63], v[96:99], v[140:143], v[60:63]
	v_mfma_f32_16x16x32_bf16 v[28:31], v[104:107], v[140:143], v[28:31]
	v_mfma_f32_16x16x32_bf16 v[56:59], v[96:99], v[148:151], v[56:59]
	v_mfma_f32_16x16x32_bf16 v[24:27], v[104:107], v[148:151], v[24:27]
	v_mfma_f32_16x16x32_bf16 v[52:55], v[96:99], v[156:159], v[52:55]
	v_mfma_f32_16x16x32_bf16 v[20:23], v[104:107], v[156:159], v[20:23]
	v_mfma_f32_16x16x32_bf16 v[48:51], v[96:99], v[168:171], v[48:51]
	v_mfma_f32_16x16x32_bf16 v[16:19], v[104:107], v[168:171], v[16:19]
	v_mfma_f32_16x16x32_bf16 v[60:63], v[100:103], v[144:147], v[60:63]
	v_mfma_f32_16x16x32_bf16 v[28:31], v[108:111], v[144:147], v[28:31]
	v_mfma_f32_16x16x32_bf16 v[56:59], v[100:103], v[152:155], v[56:59]
	v_mfma_f32_16x16x32_bf16 v[24:27], v[108:111], v[152:155], v[24:27]
	v_mfma_f32_16x16x32_bf16 v[52:55], v[100:103], v[160:163], v[52:55]
	v_mfma_f32_16x16x32_bf16 v[20:23], v[108:111], v[160:163], v[20:23]
	v_mfma_f32_16x16x32_bf16 v[48:51], v[100:103], v[188:191], v[48:51]
	v_mfma_f32_16x16x32_bf16 v[16:19], v[108:111], v[188:191], v[16:19]
	v_mfma_f32_16x16x32_bf16 v[44:47], v[112:115], v[140:143], v[44:47]
	v_mfma_f32_16x16x32_bf16 v[12:15], v[120:123], v[140:143], v[12:15]
	v_mfma_f32_16x16x32_bf16 v[40:43], v[112:115], v[148:151], v[40:43]
	v_mfma_f32_16x16x32_bf16 v[8:11], v[120:123], v[148:151], v[8:11]
	v_mfma_f32_16x16x32_bf16 v[36:39], v[112:115], v[156:159], v[36:39]
	v_mfma_f32_16x16x32_bf16 v[4:7], v[120:123], v[156:159], v[4:7]
	v_mfma_f32_16x16x32_bf16 v[32:35], v[112:115], v[168:171], v[32:35]
	v_mfma_f32_16x16x32_bf16 v[0:3], v[120:123], v[168:171], v[0:3]
	v_mfma_f32_16x16x32_bf16 v[44:47], v[116:119], v[144:147], v[44:47]
	v_mfma_f32_16x16x32_bf16 v[12:15], v[124:127], v[144:147], v[12:15]
	v_mfma_f32_16x16x32_bf16 v[40:43], v[116:119], v[152:155], v[40:43]
	v_mfma_f32_16x16x32_bf16 v[8:11], v[124:127], v[152:155], v[8:11]
	v_mfma_f32_16x16x32_bf16 v[36:39], v[116:119], v[160:163], v[36:39]
	v_mfma_f32_16x16x32_bf16 v[4:7], v[124:127], v[160:163], v[4:7]
	v_mfma_f32_16x16x32_bf16 v[32:35], v[116:119], v[188:191], v[32:35]
	v_mfma_f32_16x16x32_bf16 v[0:3], v[124:127], v[188:191], v[0:3]
	s_barrier
	s_add_i32 s52, 0, 0x18000
	s_add_i32 s53, 0, 0x1c000
	v_add_u32_e32 v108, s52, v193
	v_add_u32_e32 v124, s53, v193
	ds_read_b128 v[96:99], v108
	ds_read_b128 v[100:103], v108 offset:1024
	ds_read_b128 v[104:107], v108 offset:2048
	ds_read_b128 v[108:111], v108 offset:3072
	ds_read_b128 v[112:115], v124
	ds_read_b128 v[116:119], v124 offset:1024
	ds_read_b128 v[120:123], v124 offset:2048
	ds_read_b128 v[124:127], v124 offset:3072
	s_add_u32 s20, s26, 0x80000
	s_addc_u32 s21, s27, 0
	s_mov_b32 m0, s31
	v_lshl_add_u64 v[156:157], s[20:21], 0, v[212:213]
	ds_read_b128 v[140:143], v224 offset:32768
	ds_read_b128 v[144:147], v224 offset:33792
	ds_read_b128 v[148:151], v224 offset:34816
	ds_read_b128 v[152:155], v224 offset:35840
	ds_read_b128 v[160:163], v224 offset:36864
	ds_read_b128 v[168:171], v224 offset:37888
	ds_read_b128 v[188:191], v224 offset:38912
	ds_read_b128 v[226:229], v224 offset:39936
	global_load_lds_dwordx4 v[156:157], off
	v_lshl_add_u64 v[156:157], s[20:21], 0, v[208:209]
	s_mov_b32 m0, s34
	s_nop 0
	global_load_lds_dwordx4 v[156:157], off
	s_waitcnt vmcnt(8)
	s_waitcnt lgkmcnt(0)
	s_barrier
	s_waitcnt lgkmcnt(0)
	v_mfma_f32_16x16x32_bf16 v[156:159], v[96:99], v[140:143], v[184:187]
	v_mfma_f32_16x16x32_bf16 v[184:187], v[100:103], v[144:147], v[156:159]
	v_mfma_f32_16x16x32_bf16 v[156:159], v[96:99], v[148:151], v[180:183]
	v_mfma_f32_16x16x32_bf16 v[180:183], v[100:103], v[152:155], v[156:159]
	v_mfma_f32_16x16x32_bf16 v[156:159], v[96:99], v[160:163], v[176:179]
	v_mfma_f32_16x16x32_bf16 v[92:95], v[104:107], v[140:143], v[92:95]
	v_mfma_f32_16x16x32_bf16 v[88:91], v[104:107], v[148:151], v[88:91]
	v_mfma_f32_16x16x32_bf16 v[176:179], v[100:103], v[168:171], v[156:159]
	v_mfma_f32_16x16x32_bf16 v[84:87], v[104:107], v[160:163], v[84:87]
	v_mfma_f32_16x16x32_bf16 v[156:159], v[96:99], v[188:191], v[172:175]
	v_mfma_f32_16x16x32_bf16 v[80:83], v[104:107], v[188:191], v[80:83]
	v_mfma_f32_16x16x32_bf16 v[92:95], v[108:111], v[144:147], v[92:95]
	v_mfma_f32_16x16x32_bf16 v[88:91], v[108:111], v[152:155], v[88:91]
	v_mfma_f32_16x16x32_bf16 v[84:87], v[108:111], v[168:171], v[84:87]
	v_mfma_f32_16x16x32_bf16 v[172:175], v[100:103], v[226:229], v[156:159]
	v_mfma_f32_16x16x32_bf16 v[80:83], v[108:111], v[226:229], v[80:83]
	v_mfma_f32_16x16x32_bf16 v[156:159], v[112:115], v[140:143], v[164:167]
	v_mfma_f32_16x16x32_bf16 v[128:131], v[112:115], v[148:151], v[128:131]
	v_mfma_f32_16x16x32_bf16 v[164:167], v[116:119], v[144:147], v[156:159]
	v_mfma_f32_16x16x32_bf16 v[156:159], v[116:119], v[152:155], v[128:131]
	v_mfma_f32_16x16x32_bf16 v[128:131], v[112:115], v[160:163], v[132:135]
	v_mfma_f32_16x16x32_bf16 v[76:79], v[120:123], v[140:143], v[76:79]
	v_mfma_f32_16x16x32_bf16 v[72:75], v[120:123], v[148:151], v[72:75]
	v_mfma_f32_16x16x32_bf16 v[148:151], v[116:119], v[168:171], v[128:131]
	v_mfma_f32_16x16x32_bf16 v[68:71], v[120:123], v[160:163], v[68:71]
	v_mfma_f32_16x16x32_bf16 v[128:131], v[112:115], v[188:191], v[136:139]
	v_mfma_f32_16x16x32_bf16 v[64:67], v[120:123], v[188:191], v[64:67]
	v_mfma_f32_16x16x32_bf16 v[76:79], v[124:127], v[144:147], v[76:79]
	v_mfma_f32_16x16x32_bf16 v[72:75], v[124:127], v[152:155], v[72:75]
	v_mfma_f32_16x16x32_bf16 v[68:71], v[124:127], v[168:171], v[68:71]
	v_mfma_f32_16x16x32_bf16 v[140:143], v[116:119], v[226:229], v[128:131]
	v_mfma_f32_16x16x32_bf16 v[64:67], v[124:127], v[226:229], v[64:67]
	s_barrier
; #define PG8_STAGE(bufoff, gbase, voff) do { _Pragma("unroll") for (int _i = 0; _i < 2; ++_i) \
;         __builtin_amdgcn_global_load_lds((const unsigned*)((const char*)(gbase) + (voff)[_i]), (LAS unsigned*)(lds + (bufoff) + ldsw + _i * 8192), 16, 0, 0); } while (0)
; #define PG8_LDA(dst, b, h) do { _Pragma("unroll") for (int m = 0; m < 4; ++m) _Pragma("unroll") for (int k = 0; k < 2; ++k) dst[m][k] = *(const LAS bf16x8*)(lds + PG8_SA(b, h) + aoff + m * 2048 + k * 1024); } while (0)
; #define PG8_MMA(ai, bj, At, Bt) do { __builtin_amdgcn_s_setprio(1); _Pragma("unroll") for (int m = 0; m < 4; ++m) _Pragma("unroll") for (int n = 0; n < 2; ++n) _Pragma("unroll") for (int k = 0; k < 2; ++k) \
;         acc[ai][bj][m][n] = __builtin_amdgcn_mfma_f32_16x16x32_bf16(Bt[n][k], At[m][k], acc[ai][bj][m][n], 0, 0, 0); __builtin_amdgcn_s_setprio(0); } while (0)
; #define PG8_WAIT_V(n) asm volatile("s_waitcnt vmcnt(" #n ")" ::: "memory")
; #define PG8_WAIT_L(n) asm volatile("s_waitcnt lgkmcnt(" #n ")" ::: "memory")
; #define PG8_BAR __builtin_amdgcn_s_barrier()
; #define PG8_SCHED __builtin_amdgcn_sched_barrier(0)
; template <class Epi, bool PERMA = false, bool DUAL = false, bool ALIGN_EPI = true, bool SP2 = true>
; __device__ __forceinline__ void gemm_phase(LAS unsigned char* lds, const Gemm g, const StaticOrder& S, const Epi& E) {
;     ...
;             PG8_LDA(At, 1, 1); PG8_STAGE(PG8_SB(1, 0), b3, voffB); PG8_STAGE(PG8_SB(1, 1), b3 + hstepB, voffB); PG8_STAGE(PG8_SA(1, 0), a3, voffA);
;             PG8_WAIT_V(8); PG8_WAIT_L(0); PG8_BAR; PG8_MMA(1, 0, At, B0); PG8_MMA(1, 1, At, B1); PG8_BAR; PG8_SCHED;
;     __device__ __forceinline__ void operator()(const f32x4 (&acc)[2][2][4][2], const Unit& u, int wr, int wc, int fr, int fq) const {
;     ...
; #pragma unroll
;         for (int n = 0; n < 2; ++n) { const float* wp = cw + ch0 + 4 * n;
;             wgt[n][0] = *(const f32x4*)wp; wgt[n][1] = *(const f32x4*)(wp + 2 * DFF); wgt[n][2] = *(const f32x4*)(wp + 4 * DFF); wgt[n][3] = *(const f32x4*)(cb + ch0 + 4 * n);
;             wgt[n][4] = *(const f32x4*)(wp + DFF); wgt[n][5] = *(const f32x4*)(wp + 3 * DFF); wgt[n][6] = *(const f32x4*)(wp + 5 * DFF); wgt[n][7] = *(const f32x4*)(cb + DFF + ch0 + 4 * n); }
	s_add_i32 s20, s52, s28
	v_lshl_add_u64 v[220:221], v[220:221], 0, s[56:57]
	s_mov_b32 m0, s20
	ds_read_b128 v[128:131], v224 offset:49152
	ds_read_b128 v[132:135], v224 offset:50176
	ds_read_b128 v[136:139], v224 offset:51200
	ds_read_b128 v[144:147], v224 offset:52224
	ds_read_b128 v[152:155], v224 offset:53248
	ds_read_b128 v[160:163], v224 offset:54272
	ds_read_b128 v[168:171], v224 offset:55296
	ds_read_b128 v[188:191], v224 offset:56320
	global_load_lds_dwordx4 v[220:221], off
	s_add_i32 m0, s20, 0x2000
	s_add_u32 s20, s24, 0x80080
	v_lshl_add_u64 v[220:221], v[238:239], 0, s[56:57]
	s_addc_u32 s21, s25, 0
	s_add_i32 s24, s53, s28
	global_load_lds_dwordx4 v[220:221], off
	v_lshl_add_u64 v[220:221], s[20:21], 0, v[210:211]
	s_mov_b32 m0, s24
	s_nop 0
	global_load_lds_dwordx4 v[220:221], off
	v_lshl_add_u64 v[220:221], s[20:21], 0, v[206:207]
	s_add_i32 m0, s24, 0x2000
	s_nop 0
	global_load_lds_dwordx4 v[220:221], off
	v_lshl_add_u64 v[220:221], v[240:241], 0, s[56:57]
	s_mov_b32 m0, s35
	s_nop 0
	global_load_lds_dwordx4 v[220:221], off
	v_lshl_add_u64 v[220:221], v[242:243], 0, s[56:57]
	s_mov_b32 m0, s36
	s_nop 0
	global_load_lds_dwordx4 v[220:221], off
	s_waitcnt vmcnt(8)
	s_waitcnt lgkmcnt(0)
	s_barrier
	s_waitcnt lgkmcnt(0)
	v_mfma_f32_16x16x32_bf16 v[60:63], v[96:99], v[128:131], v[60:63]
	v_mfma_f32_16x16x32_bf16 v[28:31], v[104:107], v[128:131], v[28:31]
	v_mfma_f32_16x16x32_bf16 v[56:59], v[96:99], v[136:139], v[56:59]
	v_mfma_f32_16x16x32_bf16 v[24:27], v[104:107], v[136:139], v[24:27]
	v_mfma_f32_16x16x32_bf16 v[52:55], v[96:99], v[152:155], v[52:55]
	v_mfma_f32_16x16x32_bf16 v[20:23], v[104:107], v[152:155], v[20:23]
	v_mfma_f32_16x16x32_bf16 v[48:51], v[96:99], v[168:171], v[48:51]
	v_mfma_f32_16x16x32_bf16 v[16:19], v[104:107], v[168:171], v[16:19]
	v_mfma_f32_16x16x32_bf16 v[60:63], v[100:103], v[132:135], v[60:63]
	v_mfma_f32_16x16x32_bf16 v[28:31], v[108:111], v[132:135], v[28:31]
	v_mfma_f32_16x16x32_bf16 v[56:59], v[100:103], v[144:147], v[56:59]
	v_mfma_f32_16x16x32_bf16 v[24:27], v[108:111], v[144:147], v[24:27]
	v_mfma_f32_16x16x32_bf16 v[52:55], v[100:103], v[160:163], v[52:55]
	v_mfma_f32_16x16x32_bf16 v[20:23], v[108:111], v[160:163], v[20:23]
	v_mfma_f32_16x16x32_bf16 v[48:51], v[100:103], v[188:191], v[48:51]
	v_mfma_f32_16x16x32_bf16 v[16:19], v[108:111], v[188:191], v[16:19]
	v_mfma_f32_16x16x32_bf16 v[44:47], v[112:115], v[128:131], v[44:47]
	v_mfma_f32_16x16x32_bf16 v[12:15], v[120:123], v[128:131], v[12:15]
	v_mfma_f32_16x16x32_bf16 v[40:43], v[112:115], v[136:139], v[40:43]
	v_mfma_f32_16x16x32_bf16 v[8:11], v[120:123], v[136:139], v[8:11]
	v_mfma_f32_16x16x32_bf16 v[36:39], v[112:115], v[152:155], v[36:39]
	v_mfma_f32_16x16x32_bf16 v[4:7], v[120:123], v[152:155], v[4:7]
	v_mfma_f32_16x16x32_bf16 v[32:35], v[112:115], v[168:171], v[32:35]
	v_mfma_f32_16x16x32_bf16 v[0:3], v[120:123], v[168:171], v[0:3]
	v_mfma_f32_16x16x32_bf16 v[44:47], v[116:119], v[132:135], v[44:47]
	v_mfma_f32_16x16x32_bf16 v[12:15], v[124:127], v[132:135], v[12:15]
	v_mfma_f32_16x16x32_bf16 v[40:43], v[116:119], v[144:147], v[40:43]
	v_mfma_f32_16x16x32_bf16 v[8:11], v[124:127], v[144:147], v[8:11]
	v_mfma_f32_16x16x32_bf16 v[36:39], v[116:119], v[160:163], v[36:39]
	v_mfma_f32_16x16x32_bf16 v[4:7], v[124:127], v[160:163], v[4:7]
	v_mfma_f32_16x16x32_bf16 v[32:35], v[116:119], v[188:191], v[32:35]
	v_mfma_f32_16x16x32_bf16 v[0:3], v[124:127], v[188:191], v[0:3]
	s_add_i32 s51, s51, 2
	s_add_u32 s49, s49, 0x100
	s_addc_u32 s50, s50, 0
	s_cmp_gt_u32 s51, 29
	s_mov_b64 s[20:21], s[22:23]
	s_barrier
	s_cbranch_scc0 .LBB0_528
	v_lshl_or_b32 v220, s38, 7, v214
	v_ashrrev_i32_e32 v221, 31, v220
	v_lshlrev_b64 v[96:97], 2, v[220:221]
	v_lshl_add_u64 v[112:113], s[2:3], 0, v[96:97]
	v_add_co_u32_e32 v102, vcc, s72, v112
	s_mov_b64 s[20:21], 0xb000
	s_nop 0
	v_addc_co_u32_e32 v103, vcc, 0, v113, vcc
	s_mov_b32 s13, 0x16000
	v_lshl_add_u64 v[100:101], v[112:113], 0, s[20:21]
	s_mov_b64 s[20:21], 0x16000
	v_add_co_u32_e32 v106, vcc, s13, v112
	s_nop 0
	v_lshl_add_u64 v[104:105], v[112:113], 0, s[20:21]
	v_addc_co_u32_e32 v107, vcc, 0, v113, vcc
	v_lshl_add_u64 v[114:115], s[6:7], 0, v[96:97]
	v_lshl_add_u64 v[188:189], s[10:11], 0, v[96:97]
	global_load_dwordx4 v[96:99], v[112:113], off offset:16
	global_load_dwordx4 v[128:131], v[112:113], off
	global_load_dwordx4 v[132:135], v[102:103], off
	s_nop 0
	global_load_dwordx4 v[100:103], v[100:101], off offset:16
	s_nop 0
	global_load_dwordx4 v[136:139], v[106:107], off
	s_nop 0
	global_load_dwordx4 v[104:107], v[104:105], off offset:16
	s_nop 0
	global_load_dwordx4 v[108:111], v[114:115], off offset:16
	global_load_dwordx4 v[144:147], v[114:115], off
	s_movk_i32 s13, 0x5000
	v_add_co_u32_e32 v116, vcc, s13, v112
	s_mov_b64 s[20:21], 0x5800
	s_nop 0
	v_addc_co_u32_e32 v117, vcc, 0, v113, vcc
	s_mov_b32 s13, 0x10000
	v_lshl_add_u64 v[114:115], v[112:113], 0, s[20:21]
	s_mov_b64 s[20:21], 0x10800
	v_add_co_u32_e32 v120, vcc, s13, v112
	global_load_dwordx4 v[160:163], v[116:117], off offset:2048
	s_nop 0
	global_load_dwordx4 v[116:119], v[114:115], off offset:16
	v_lshl_add_u64 v[114:115], v[112:113], 0, s[20:21]
	v_addc_co_u32_e32 v121, vcc, 0, v113, vcc
	s_mov_b64 s[20:21], 0x1b800
	s_mov_b32 s13, 0x1b000
	global_load_dwordx4 v[168:171], v[120:121], off offset:2048
	s_nop 0
	global_load_dwordx4 v[120:123], v[114:115], off offset:16
	v_lshl_add_u64 v[114:115], v[112:113], 0, s[20:21]
	v_add_co_u32_e32 v112, vcc, s13, v112
	s_nop 0
	v_addc_co_u32_e32 v113, vcc, 0, v113, vcc
	global_load_dwordx4 v[152:155], v[112:113], off offset:2048
	s_nop 0
	global_load_dwordx4 v[112:115], v[114:115], off offset:16
	s_nop 0
	global_load_dwordx4 v[124:127], v[188:189], off offset:16
	s_nop 0
	global_load_dwordx4 v[188:191], v[188:189], off
	s_and_b64 vcc, exec, s[4:5]
	s_cbranch_vccz .LBB0_531
	s_barrier

; #define PG8_STAGE(bufoff, gbase, voff) do { _Pragma("unroll") for (int _i = 0; _i < 2; ++_i) \
;         __builtin_amdgcn_global_load_lds((const unsigned*)((const char*)(gbase) + (voff)[_i]), (LAS unsigned*)(lds + (bufoff) + ldsw + _i * 8192), 16, 0, 0); } while (0)
; #define PG8_LDA(dst, b, h) do { _Pragma("unroll") for (int m = 0; m < 4; ++m) _Pragma("unroll") for (int k = 0; k < 2; ++k) dst[m][k] = *(const LAS bf16x8*)(lds + PG8_SA(b, h) + aoff + m * 2048 + k * 1024); } while (0)
; #define PG8_LDB(dst, b, h) do { _Pragma("unroll") for (int n = 0; n < 2; ++n) _Pragma("unroll") for (int k = 0; k < 2; ++k) dst[n][k] = *(const LAS bf16x8*)(lds + PG8_SB(b, h) + boff + n * 2048 + k * 1024); } while (0)
; #define PG8_MMA(ai, bj, At, Bt) do { __builtin_amdgcn_s_setprio(1); _Pragma("unroll") for (int m = 0; m < 4; ++m) _Pragma("unroll") for (int n = 0; n < 2; ++n) _Pragma("unroll") for (int k = 0; k < 2; ++k) \
;         acc[ai][bj][m][n] = __builtin_amdgcn_mfma_f32_16x16x32_bf16(Bt[n][k], At[m][k], acc[ai][bj][m][n], 0, 0, 0); __builtin_amdgcn_s_setprio(0); } while (0)
; #define PG8_WAIT_V(n) asm volatile("s_waitcnt vmcnt(" #n ")" ::: "memory")
; #define PG8_WAIT_L(n) asm volatile("s_waitcnt lgkmcnt(" #n ")" ::: "memory")
; #define PG8_BAR __builtin_amdgcn_s_barrier()
; #define PG8_SCHED __builtin_amdgcn_sched_barrier(0)
; template <class Epi, bool PERMA = false, bool DUAL = false, bool ALIGN_EPI = true, bool SP2 = true>
; __device__ __forceinline__ void gemm_phase(LAS unsigned char* lds, const Gemm g, const StaticOrder& S, const Epi& E) {
;     ...
;             const bool last = (t == nt - 2);
;             const char* a1 = cA + (size_t)(t + 1) * kstep;
;             const char* a2 = last ? nA : cA + (size_t)(t + 2) * kstep; const char* b2 = last ? nB : cB + (size_t)(t + 2) * kstep;
;             const char* a3 = a2 + kstep; const char* b3 = b2 + kstep;
;             if constexpr (SP2) {
;             PG8_LDB(B0, 0, 0); PG8_LDB(B1, 0, 1); PG8_SCHED; PG8_LDA(At, 0, 0); PG8_STAGE(PG8_SA(1, 1), a1 + hstepA, voffA);
;             PG8_WAIT_V(8); PG8_WAIT_L(0); PG8_BAR; PG8_MMA(0, 0, At, B0); PG8_MMA(0, 1, At, B1); PG8_BAR; PG8_SCHED;
;             PG8_LDA(At, 0, 1); PG8_STAGE(PG8_SB(0, 0), b2, voffB); PG8_STAGE(PG8_SB(0, 1), b2 + hstepB, voffB); PG8_STAGE(PG8_SA(0, 0), a2, voffA);
.LBB0_675:
	s_add_u32 s14, s12, 0x100
	s_addc_u32 s15, s13, 0
	s_add_i32 s36, 0, 0x10000
	s_cmpk_eq_i32 s33, 0x54
	s_cselect_b32 s19, s1, s15
	s_cselect_b32 s18, s0, s14
	s_cselect_b32 s17, s7, s11
	s_cselect_b32 s16, s6, s9
	s_add_i32 s37, 0, 0x14000
	v_add_u32_e32 v116, s36, v193
	v_add_u32_e32 v156, s37, v193
	ds_read_b128 v[104:107], v116
	ds_read_b128 v[108:111], v116 offset:1024
	ds_read_b128 v[112:115], v116 offset:2048
	ds_read_b128 v[116:119], v116 offset:3072
	ds_read_b128 v[144:147], v156
	ds_read_b128 v[148:151], v156 offset:1024
	ds_read_b128 v[152:155], v156 offset:2048
	ds_read_b128 v[156:159], v156 offset:3072
	v_lshl_add_u64 v[206:207], s[12:13], 0, v[180:181]
	s_add_i32 m0, s21, 0xc000
	ds_read_b128 v[184:187], v212
	ds_read_b128 v[188:191], v212 offset:1024
	ds_read_b128 v[214:217], v212 offset:2048
	ds_read_b128 v[218:221], v212 offset:3072
	ds_read_b128 v[222:225], v212 offset:4096
	ds_read_b128 v[226:229], v212 offset:5120
	ds_read_b128 v[238:241], v212 offset:6144
	ds_read_b128 v[242:245], v212 offset:7168
	global_load_lds_dwordx4 v[206:207], off
	v_lshl_add_u64 v[206:207], s[12:13], 0, v[182:183]
	s_add_i32 m0, s21, 0xe000
	s_nop 0
	global_load_lds_dwordx4 v[206:207], off
	s_waitcnt vmcnt(8)
	s_waitcnt lgkmcnt(0)
	s_barrier
	s_waitcnt lgkmcnt(0)
	v_mfma_f32_16x16x32_bf16 v[140:143], v[104:107], v[184:187], v[140:143]
	v_mfma_f32_16x16x32_bf16 v[136:139], v[112:115], v[184:187], v[136:139]
	v_mfma_f32_16x16x32_bf16 v[124:127], v[104:107], v[214:217], v[124:127]
	v_mfma_f32_16x16x32_bf16 v[120:123], v[112:115], v[214:217], v[120:123]
	v_mfma_f32_16x16x32_bf16 v[92:95], v[104:107], v[222:225], v[92:95]
	v_mfma_f32_16x16x32_bf16 v[88:91], v[112:115], v[222:225], v[88:91]
	v_mfma_f32_16x16x32_bf16 v[76:79], v[104:107], v[238:241], v[76:79]
	v_mfma_f32_16x16x32_bf16 v[72:75], v[112:115], v[238:241], v[72:75]
	v_mfma_f32_16x16x32_bf16 v[140:143], v[108:111], v[188:191], v[140:143]
	v_mfma_f32_16x16x32_bf16 v[136:139], v[116:119], v[188:191], v[136:139]
	v_mfma_f32_16x16x32_bf16 v[124:127], v[108:111], v[218:221], v[124:127]
	v_mfma_f32_16x16x32_bf16 v[120:123], v[116:119], v[218:221], v[120:123]
	v_mfma_f32_16x16x32_bf16 v[92:95], v[108:111], v[226:229], v[92:95]
	v_mfma_f32_16x16x32_bf16 v[88:91], v[116:119], v[226:229], v[88:91]
	v_mfma_f32_16x16x32_bf16 v[76:79], v[108:111], v[242:245], v[76:79]
	v_mfma_f32_16x16x32_bf16 v[72:75], v[116:119], v[242:245], v[72:75]
	v_mfma_f32_16x16x32_bf16 v[132:135], v[144:147], v[184:187], v[132:135]
	v_mfma_f32_16x16x32_bf16 v[128:131], v[152:155], v[184:187], v[128:131]
	v_mfma_f32_16x16x32_bf16 v[100:103], v[144:147], v[214:217], v[100:103]
	v_mfma_f32_16x16x32_bf16 v[96:99], v[152:155], v[214:217], v[96:99]
	v_mfma_f32_16x16x32_bf16 v[84:87], v[144:147], v[222:225], v[84:87]
	v_mfma_f32_16x16x32_bf16 v[80:83], v[152:155], v[222:225], v[80:83]
	v_mfma_f32_16x16x32_bf16 v[68:71], v[144:147], v[238:241], v[68:71]
	v_mfma_f32_16x16x32_bf16 v[64:67], v[152:155], v[238:241], v[64:67]
	v_mfma_f32_16x16x32_bf16 v[132:135], v[148:151], v[188:191], v[132:135]
	v_mfma_f32_16x16x32_bf16 v[128:131], v[156:159], v[188:191], v[128:131]
	v_mfma_f32_16x16x32_bf16 v[100:103], v[148:151], v[218:221], v[100:103]
	v_mfma_f32_16x16x32_bf16 v[96:99], v[156:159], v[218:221], v[96:99]
	v_mfma_f32_16x16x32_bf16 v[84:87], v[148:151], v[226:229], v[84:87]
	v_mfma_f32_16x16x32_bf16 v[80:83], v[156:159], v[226:229], v[80:83]
	v_mfma_f32_16x16x32_bf16 v[68:71], v[148:151], v[242:245], v[68:71]
	v_mfma_f32_16x16x32_bf16 v[64:67], v[156:159], v[242:245], v[64:67]
	s_barrier
	s_add_i32 s12, s36, s20
	v_lshl_add_u64 v[206:207], s[16:17], 0, v[164:165]
	s_mov_b32 m0, s12
	ds_read_b128 v[184:187], v212 offset:16384
	ds_read_b128 v[188:191], v212 offset:17408
	ds_read_b128 v[214:217], v212 offset:18432
	ds_read_b128 v[218:221], v212 offset:19456
	ds_read_b128 v[222:225], v212 offset:20480
	ds_read_b128 v[226:229], v212 offset:21504
	ds_read_b128 v[238:241], v212 offset:22528
	ds_read_b128 v[242:245], v212 offset:23552
	global_load_lds_dwordx4 v[206:207], off
	s_add_i32 m0, s12, 0x2000
	s_add_u32 s12, s16, 0x160000
	v_lshl_add_u64 v[246:247], s[16:17], 0, v[160:161]
	s_addc_u32 s13, s17, 0
	s_add_i32 s36, s37, s20
	global_load_lds_dwordx4 v[246:247], off
	v_lshl_add_u64 v[248:249], s[12:13], 0, v[164:165]
	s_mov_b32 m0, s36
	v_lshl_add_u64 v[194:195], s[18:19], 0, v[162:163]
	global_load_lds_dwordx4 v[248:249], off
	v_lshl_add_u64 v[248:249], s[12:13], 0, v[160:161]
	s_add_i32 m0, s36, 0x2000
	s_nop 0
	global_load_lds_dwordx4 v[248:249], off
	v_lshl_add_u64 v[248:249], s[18:19], 0, v[166:167]
	s_mov_b32 m0, s21
	s_nop 0
	global_load_lds_dwordx4 v[248:249], off
	s_mov_b32 m0, s22
	s_nop 0
	global_load_lds_dwordx4 v[194:195], off
	s_waitcnt vmcnt(8)
	s_waitcnt lgkmcnt(0)
	s_barrier
; #define PG8_STAGE(bufoff, gbase, voff) do { _Pragma("unroll") for (int _i = 0; _i < 2; ++_i) \
;         __builtin_amdgcn_global_load_lds((const unsigned*)((const char*)(gbase) + (voff)[_i]), (LAS unsigned*)(lds + (bufoff) + ldsw + _i * 8192), 16, 0, 0); } while (0)
; #define PG8_LDA(dst, b, h) do { _Pragma("unroll") for (int m = 0; m < 4; ++m) _Pragma("unroll") for (int k = 0; k < 2; ++k) dst[m][k] = *(const LAS bf16x8*)(lds + PG8_SA(b, h) + aoff + m * 2048 + k * 1024); } while (0)
; #define PG8_LDB(dst, b, h) do { _Pragma("unroll") for (int n = 0; n < 2; ++n) _Pragma("unroll") for (int k = 0; k < 2; ++k) dst[n][k] = *(const LAS bf16x8*)(lds + PG8_SB(b, h) + boff + n * 2048 + k * 1024); } while (0)
; #define PG8_MMA(ai, bj, At, Bt) do { __builtin_amdgcn_s_setprio(1); _Pragma("unroll") for (int m = 0; m < 4; ++m) _Pragma("unroll") for (int n = 0; n < 2; ++n) _Pragma("unroll") for (int k = 0; k < 2; ++k) \
;         acc[ai][bj][m][n] = __builtin_amdgcn_mfma_f32_16x16x32_bf16(Bt[n][k], At[m][k], acc[ai][bj][m][n], 0, 0, 0); __builtin_amdgcn_s_setprio(0); } while (0)
; #define PG8_WAIT_V(n) asm volatile("s_waitcnt vmcnt(" #n ")" ::: "memory")
; #define PG8_WAIT_L(n) asm volatile("s_waitcnt lgkmcnt(" #n ")" ::: "memory")
; #define PG8_BAR __builtin_amdgcn_s_barrier()
; #define PG8_SCHED __builtin_amdgcn_sched_barrier(0)
; template <class Epi, bool PERMA = false, bool DUAL = false, bool ALIGN_EPI = true, bool SP2 = true>
; __device__ __forceinline__ void gemm_phase(LAS unsigned char* lds, const Gemm g, const StaticOrder& S, const Epi& E) {
;     ...
;             PG8_WAIT_V(8); PG8_WAIT_L(0); PG8_BAR; PG8_MMA(1, 0, At, B0); PG8_MMA(1, 1, At, B1); PG8_BAR; PG8_SCHED;
;             PG8_LDB(B0, 1, 0); PG8_LDB(B1, 1, 1); PG8_SCHED; PG8_LDA(At, 1, 0); PG8_STAGE(PG8_SA(0, 1), a2 + hstepA, voffA);
;             PG8_WAIT_V(8); PG8_WAIT_L(0); PG8_BAR; PG8_MMA(0, 0, At, B0); PG8_MMA(0, 1, At, B1); PG8_BAR; PG8_SCHED;
	s_waitcnt lgkmcnt(0)
	v_mfma_f32_16x16x32_bf16 v[60:63], v[104:107], v[184:187], v[60:63]
	v_mfma_f32_16x16x32_bf16 v[56:59], v[112:115], v[184:187], v[56:59]
	v_mfma_f32_16x16x32_bf16 v[44:47], v[104:107], v[214:217], v[44:47]
	v_mfma_f32_16x16x32_bf16 v[40:43], v[112:115], v[214:217], v[40:43]
	v_mfma_f32_16x16x32_bf16 v[28:31], v[104:107], v[222:225], v[28:31]
	v_mfma_f32_16x16x32_bf16 v[24:27], v[112:115], v[222:225], v[24:27]
	v_mfma_f32_16x16x32_bf16 v[12:15], v[104:107], v[238:241], v[12:15]
	v_mfma_f32_16x16x32_bf16 v[8:11], v[112:115], v[238:241], v[8:11]
	v_mfma_f32_16x16x32_bf16 v[60:63], v[108:111], v[188:191], v[60:63]
	v_mfma_f32_16x16x32_bf16 v[56:59], v[116:119], v[188:191], v[56:59]
	v_mfma_f32_16x16x32_bf16 v[44:47], v[108:111], v[218:221], v[44:47]
	v_mfma_f32_16x16x32_bf16 v[40:43], v[116:119], v[218:221], v[40:43]
	v_mfma_f32_16x16x32_bf16 v[28:31], v[108:111], v[226:229], v[28:31]
	v_mfma_f32_16x16x32_bf16 v[24:27], v[116:119], v[226:229], v[24:27]
	v_mfma_f32_16x16x32_bf16 v[12:15], v[108:111], v[242:245], v[12:15]
	v_mfma_f32_16x16x32_bf16 v[8:11], v[116:119], v[242:245], v[8:11]
	v_mfma_f32_16x16x32_bf16 v[52:55], v[144:147], v[184:187], v[52:55]
	v_mfma_f32_16x16x32_bf16 v[48:51], v[152:155], v[184:187], v[48:51]
	v_mfma_f32_16x16x32_bf16 v[36:39], v[144:147], v[214:217], v[36:39]
	v_mfma_f32_16x16x32_bf16 v[32:35], v[152:155], v[214:217], v[32:35]
	v_mfma_f32_16x16x32_bf16 v[20:23], v[144:147], v[222:225], v[20:23]
	v_mfma_f32_16x16x32_bf16 v[16:19], v[152:155], v[222:225], v[16:19]
	v_mfma_f32_16x16x32_bf16 v[4:7], v[144:147], v[238:241], v[4:7]
	v_mfma_f32_16x16x32_bf16 v[0:3], v[152:155], v[238:241], v[0:3]
	v_mfma_f32_16x16x32_bf16 v[52:55], v[148:151], v[188:191], v[52:55]
	v_mfma_f32_16x16x32_bf16 v[48:51], v[156:159], v[188:191], v[48:51]
	v_mfma_f32_16x16x32_bf16 v[36:39], v[148:151], v[218:221], v[36:39]
	v_mfma_f32_16x16x32_bf16 v[32:35], v[156:159], v[218:221], v[32:35]
	v_mfma_f32_16x16x32_bf16 v[20:23], v[148:151], v[226:229], v[20:23]
	v_mfma_f32_16x16x32_bf16 v[16:19], v[156:159], v[226:229], v[16:19]
	v_mfma_f32_16x16x32_bf16 v[4:7], v[148:151], v[242:245], v[4:7]
	v_mfma_f32_16x16x32_bf16 v[0:3], v[156:159], v[242:245], v[0:3]
	s_barrier
	s_add_i32 s36, 0, 0x18000
	s_add_i32 s37, 0, 0x1c000
	v_add_u32_e32 v116, s36, v193
	v_add_u32_e32 v156, s37, v193
	ds_read_b128 v[104:107], v116
	ds_read_b128 v[108:111], v116 offset:1024
	ds_read_b128 v[112:115], v116 offset:2048
	ds_read_b128 v[116:119], v116 offset:3072
	ds_read_b128 v[144:147], v156
	ds_read_b128 v[148:151], v156 offset:1024
	ds_read_b128 v[152:155], v156 offset:2048
	ds_read_b128 v[156:159], v156 offset:3072
	s_add_u32 s12, s18, 0x160000
	s_addc_u32 s13, s19, 0
	s_mov_b32 m0, s23
	v_lshl_add_u64 v[196:197], s[12:13], 0, v[166:167]
	ds_read_b128 v[184:187], v212 offset:32768
	ds_read_b128 v[188:191], v212 offset:33792
	ds_read_b128 v[214:217], v212 offset:34816
	ds_read_b128 v[218:221], v212 offset:35840
	ds_read_b128 v[222:225], v212 offset:36864
	ds_read_b128 v[226:229], v212 offset:37888
	ds_read_b128 v[238:241], v212 offset:38912
	ds_read_b128 v[242:245], v212 offset:39936
	global_load_lds_dwordx4 v[196:197], off
	v_lshl_add_u64 v[196:197], s[12:13], 0, v[162:163]
	s_mov_b32 m0, s24
	s_nop 0
	global_load_lds_dwordx4 v[196:197], off
	s_waitcnt vmcnt(8)
	s_waitcnt lgkmcnt(0)
	s_barrier
	s_waitcnt lgkmcnt(0)
	v_mfma_f32_16x16x32_bf16 v[140:143], v[104:107], v[184:187], v[140:143]
	v_mfma_f32_16x16x32_bf16 v[136:139], v[112:115], v[184:187], v[136:139]
	v_mfma_f32_16x16x32_bf16 v[124:127], v[104:107], v[214:217], v[124:127]
	v_mfma_f32_16x16x32_bf16 v[120:123], v[112:115], v[214:217], v[120:123]
	v_mfma_f32_16x16x32_bf16 v[92:95], v[104:107], v[222:225], v[92:95]
	v_mfma_f32_16x16x32_bf16 v[88:91], v[112:115], v[222:225], v[88:91]
	v_mfma_f32_16x16x32_bf16 v[76:79], v[104:107], v[238:241], v[76:79]
	v_mfma_f32_16x16x32_bf16 v[72:75], v[112:115], v[238:241], v[72:75]
	v_mfma_f32_16x16x32_bf16 v[140:143], v[108:111], v[188:191], v[140:143]
	v_mfma_f32_16x16x32_bf16 v[136:139], v[116:119], v[188:191], v[136:139]
	v_mfma_f32_16x16x32_bf16 v[124:127], v[108:111], v[218:221], v[124:127]
	v_mfma_f32_16x16x32_bf16 v[120:123], v[116:119], v[218:221], v[120:123]
	v_mfma_f32_16x16x32_bf16 v[92:95], v[108:111], v[226:229], v[92:95]
	v_mfma_f32_16x16x32_bf16 v[88:91], v[116:119], v[226:229], v[88:91]
	v_mfma_f32_16x16x32_bf16 v[76:79], v[108:111], v[242:245], v[76:79]
	v_mfma_f32_16x16x32_bf16 v[72:75], v[116:119], v[242:245], v[72:75]
	v_mfma_f32_16x16x32_bf16 v[132:135], v[144:147], v[184:187], v[132:135]
	v_mfma_f32_16x16x32_bf16 v[128:131], v[152:155], v[184:187], v[128:131]
	v_mfma_f32_16x16x32_bf16 v[100:103], v[144:147], v[214:217], v[100:103]
	v_mfma_f32_16x16x32_bf16 v[96:99], v[152:155], v[214:217], v[96:99]
	v_mfma_f32_16x16x32_bf16 v[84:87], v[144:147], v[222:225], v[84:87]
	v_mfma_f32_16x16x32_bf16 v[80:83], v[152:155], v[222:225], v[80:83]
	v_mfma_f32_16x16x32_bf16 v[68:71], v[144:147], v[238:241], v[68:71]
	v_mfma_f32_16x16x32_bf16 v[64:67], v[152:155], v[238:241], v[64:67]
	v_mfma_f32_16x16x32_bf16 v[132:135], v[148:151], v[188:191], v[132:135]
	v_mfma_f32_16x16x32_bf16 v[128:131], v[156:159], v[188:191], v[128:131]
	v_mfma_f32_16x16x32_bf16 v[100:103], v[148:151], v[218:221], v[100:103]
	v_mfma_f32_16x16x32_bf16 v[96:99], v[156:159], v[218:221], v[96:99]
	v_mfma_f32_16x16x32_bf16 v[84:87], v[148:151], v[226:229], v[84:87]
	v_mfma_f32_16x16x32_bf16 v[80:83], v[156:159], v[226:229], v[80:83]
	v_mfma_f32_16x16x32_bf16 v[68:71], v[148:151], v[242:245], v[68:71]
	v_mfma_f32_16x16x32_bf16 v[64:67], v[156:159], v[242:245], v[64:67]
	s_barrier
; #define PG8_STAGE(bufoff, gbase, voff) do { _Pragma("unroll") for (int _i = 0; _i < 2; ++_i) \
;         __builtin_amdgcn_global_load_lds((const unsigned*)((const char*)(gbase) + (voff)[_i]), (LAS unsigned*)(lds + (bufoff) + ldsw + _i * 8192), 16, 0, 0); } while (0)
; #define PG8_LDA(dst, b, h) do { _Pragma("unroll") for (int m = 0; m < 4; ++m) _Pragma("unroll") for (int k = 0; k < 2; ++k) dst[m][k] = *(const LAS bf16x8*)(lds + PG8_SA(b, h) + aoff + m * 2048 + k * 1024); } while (0)
; #define PG8_MMA(ai, bj, At, Bt) do { __builtin_amdgcn_s_setprio(1); _Pragma("unroll") for (int m = 0; m < 4; ++m) _Pragma("unroll") for (int n = 0; n < 2; ++n) _Pragma("unroll") for (int k = 0; k < 2; ++k) \
;         acc[ai][bj][m][n] = __builtin_amdgcn_mfma_f32_16x16x32_bf16(Bt[n][k], At[m][k], acc[ai][bj][m][n], 0, 0, 0); __builtin_amdgcn_s_setprio(0); } while (0)
; #define PG8_WAIT_V(n) asm volatile("s_waitcnt vmcnt(" #n ")" ::: "memory")
; #define PG8_WAIT_L(n) asm volatile("s_waitcnt lgkmcnt(" #n ")" ::: "memory")
; #define PG8_BAR __builtin_amdgcn_s_barrier()
; #define PG8_SCHED __builtin_amdgcn_sched_barrier(0)
; template <class Epi, bool PERMA = false, bool DUAL = false, bool ALIGN_EPI = true, bool SP2 = true>
; __device__ __forceinline__ void gemm_phase(LAS unsigned char* lds, const Gemm g, const StaticOrder& S, const Epi& E) {
;     ...
;             PG8_LDA(At, 1, 1); PG8_STAGE(PG8_SB(1, 0), b3, voffB); PG8_STAGE(PG8_SB(1, 1), b3 + hstepB, voffB); PG8_STAGE(PG8_SA(1, 0), a3, voffA);
;             PG8_WAIT_V(8); PG8_WAIT_L(0); PG8_BAR; PG8_MMA(1, 0, At, B0); PG8_MMA(1, 1, At, B1); PG8_BAR; PG8_SCHED;
;     ...
;         if constexpr (ALIGN_EPI) { if (wr == 0) PG8_BAR; }
	s_add_i32 s12, s36, s20
	v_lshl_add_u64 v[196:197], v[206:207], 0, s[38:39]
	s_mov_b32 m0, s12
	ds_read_b128 v[184:187], v212 offset:49152
	ds_read_b128 v[188:191], v212 offset:50176
	ds_read_b128 v[214:217], v212 offset:51200
	ds_read_b128 v[218:221], v212 offset:52224
	ds_read_b128 v[222:225], v212 offset:53248
	ds_read_b128 v[226:229], v212 offset:54272
	ds_read_b128 v[238:241], v212 offset:55296
	ds_read_b128 v[242:245], v212 offset:56320
	global_load_lds_dwordx4 v[196:197], off
	s_add_i32 m0, s12, 0x2000
	s_add_u32 s12, s16, 0x160080
	v_lshl_add_u64 v[196:197], v[246:247], 0, s[38:39]
	s_addc_u32 s13, s17, 0
	s_add_i32 s16, s37, s20
	global_load_lds_dwordx4 v[196:197], off
	v_lshl_add_u64 v[196:197], s[12:13], 0, v[164:165]
	s_mov_b32 m0, s16
	v_lshl_add_u64 v[194:195], v[194:195], 0, s[38:39]
	global_load_lds_dwordx4 v[196:197], off
	v_lshl_add_u64 v[196:197], s[12:13], 0, v[160:161]
	s_add_i32 m0, s16, 0x2000
	s_nop 0
	global_load_lds_dwordx4 v[196:197], off
	v_lshl_add_u64 v[196:197], v[248:249], 0, s[38:39]
	s_mov_b32 m0, s29
	s_nop 0
	global_load_lds_dwordx4 v[196:197], off
	s_mov_b32 m0, s30
	s_nop 0
	global_load_lds_dwordx4 v[194:195], off
	s_waitcnt vmcnt(8)
	s_waitcnt lgkmcnt(0)
	s_barrier
	s_waitcnt lgkmcnt(0)
	v_mfma_f32_16x16x32_bf16 v[60:63], v[104:107], v[184:187], v[60:63]
	v_mfma_f32_16x16x32_bf16 v[56:59], v[112:115], v[184:187], v[56:59]
	v_mfma_f32_16x16x32_bf16 v[44:47], v[104:107], v[214:217], v[44:47]
	v_mfma_f32_16x16x32_bf16 v[40:43], v[112:115], v[214:217], v[40:43]
	v_mfma_f32_16x16x32_bf16 v[28:31], v[104:107], v[222:225], v[28:31]
	v_mfma_f32_16x16x32_bf16 v[24:27], v[112:115], v[222:225], v[24:27]
	v_mfma_f32_16x16x32_bf16 v[12:15], v[104:107], v[238:241], v[12:15]
	v_mfma_f32_16x16x32_bf16 v[8:11], v[112:115], v[238:241], v[8:11]
	v_mfma_f32_16x16x32_bf16 v[60:63], v[108:111], v[188:191], v[60:63]
	v_mfma_f32_16x16x32_bf16 v[56:59], v[116:119], v[188:191], v[56:59]
	v_mfma_f32_16x16x32_bf16 v[44:47], v[108:111], v[218:221], v[44:47]
	v_mfma_f32_16x16x32_bf16 v[40:43], v[116:119], v[218:221], v[40:43]
	v_mfma_f32_16x16x32_bf16 v[28:31], v[108:111], v[226:229], v[28:31]
	v_mfma_f32_16x16x32_bf16 v[24:27], v[116:119], v[226:229], v[24:27]
	v_mfma_f32_16x16x32_bf16 v[12:15], v[108:111], v[242:245], v[12:15]
	v_mfma_f32_16x16x32_bf16 v[8:11], v[116:119], v[242:245], v[8:11]
	v_mfma_f32_16x16x32_bf16 v[52:55], v[144:147], v[184:187], v[52:55]
	v_mfma_f32_16x16x32_bf16 v[48:51], v[152:155], v[184:187], v[48:51]
	v_mfma_f32_16x16x32_bf16 v[36:39], v[144:147], v[214:217], v[36:39]
	v_mfma_f32_16x16x32_bf16 v[32:35], v[152:155], v[214:217], v[32:35]
	v_mfma_f32_16x16x32_bf16 v[20:23], v[144:147], v[222:225], v[20:23]
	v_mfma_f32_16x16x32_bf16 v[16:19], v[152:155], v[222:225], v[16:19]
	v_mfma_f32_16x16x32_bf16 v[4:7], v[144:147], v[238:241], v[4:7]
	v_mfma_f32_16x16x32_bf16 v[0:3], v[152:155], v[238:241], v[0:3]
	v_mfma_f32_16x16x32_bf16 v[52:55], v[148:151], v[188:191], v[52:55]
	v_mfma_f32_16x16x32_bf16 v[48:51], v[156:159], v[188:191], v[48:51]
	v_mfma_f32_16x16x32_bf16 v[36:39], v[148:151], v[218:221], v[36:39]
	v_mfma_f32_16x16x32_bf16 v[32:35], v[156:159], v[218:221], v[32:35]
	v_mfma_f32_16x16x32_bf16 v[20:23], v[148:151], v[226:229], v[20:23]
	v_mfma_f32_16x16x32_bf16 v[16:19], v[156:159], v[226:229], v[16:19]
	v_mfma_f32_16x16x32_bf16 v[4:7], v[148:151], v[242:245], v[4:7]
	v_mfma_f32_16x16x32_bf16 v[0:3], v[156:159], v[242:245], v[0:3]
	s_add_i32 s33, s33, 2
	s_add_u32 s9, s9, 0x100
	s_addc_u32 s11, s11, 0
	s_cmpk_gt_u32 s33, 0x55
	s_mov_b64 s[12:13], s[14:15]
	s_barrier
	s_cbranch_scc0 .LBB0_675
	s_and_b64 vcc, exec, s[4:5]
	s_cbranch_vccz .LBB0_678
	s_barrier

; #define PG8_STAGE(bufoff, gbase, voff) do { _Pragma("unroll") for (int _i = 0; _i < 2; ++_i) \
;         __builtin_amdgcn_global_load_lds((const unsigned*)((const char*)(gbase) + (voff)[_i]), (LAS unsigned*)(lds + (bufoff) + ldsw + _i * 8192), 16, 0, 0); } while (0)
; #define PG8_LDA(dst, b, h) do { _Pragma("unroll") for (int m = 0; m < 4; ++m) _Pragma("unroll") for (int k = 0; k < 2; ++k) dst[m][k] = *(const LAS bf16x8*)(lds + PG8_SA(b, h) + aoff + m * 2048 + k * 1024); } while (0)
; #define PG8_LDB(dst, b, h) do { _Pragma("unroll") for (int n = 0; n < 2; ++n) _Pragma("unroll") for (int k = 0; k < 2; ++k) dst[n][k] = *(const LAS bf16x8*)(lds + PG8_SB(b, h) + boff + n * 2048 + k * 1024); } while (0)
; #define PG8_MMA(ai, bj, At, Bt) do { __builtin_amdgcn_s_setprio(1); _Pragma("unroll") for (int m = 0; m < 4; ++m) _Pragma("unroll") for (int n = 0; n < 2; ++n) _Pragma("unroll") for (int k = 0; k < 2; ++k) \
;         acc[ai][bj][m][n] = __builtin_amdgcn_mfma_f32_16x16x32_bf16(Bt[n][k], At[m][k], acc[ai][bj][m][n], 0, 0, 0); __builtin_amdgcn_s_setprio(0); } while (0)
; #define PG8_WAIT_V(n) asm volatile("s_waitcnt vmcnt(" #n ")" ::: "memory")
; #define PG8_WAIT_L(n) asm volatile("s_waitcnt lgkmcnt(" #n ")" ::: "memory")
; #define PG8_BAR __builtin_amdgcn_s_barrier()
; #define PG8_SCHED __builtin_amdgcn_sched_barrier(0)
; template <class Epi, bool PERMA = false, bool DUAL = false, bool ALIGN_EPI = true, bool SP2 = true>
; __device__ __forceinline__ void gemm_phase(LAS unsigned char* lds, const Gemm g, const StaticOrder& S, const Epi& E) {
;     ...
;             const bool last = (t == nt - 2);
;             const char* a1 = cA + (size_t)(t + 1) * kstep;
;             const char* a2 = last ? nA : cA + (size_t)(t + 2) * kstep; const char* b2 = last ? nB : cB + (size_t)(t + 2) * kstep;
;             const char* a3 = a2 + kstep; const char* b3 = b2 + kstep;
;             if constexpr (SP2) {
;             PG8_LDB(B0, 0, 0); PG8_LDB(B1, 0, 1); PG8_SCHED; PG8_LDA(At, 0, 0); PG8_STAGE(PG8_SA(1, 1), a1 + hstepA, voffA);
;             PG8_WAIT_V(8); PG8_WAIT_L(0); PG8_BAR; PG8_MMA(0, 0, At, B0); PG8_MMA(0, 1, At, B1); PG8_BAR; PG8_SCHED;
;             PG8_LDA(At, 0, 1); PG8_STAGE(PG8_SB(0, 0), b2, voffB); PG8_STAGE(PG8_SB(0, 1), b2 + hstepB, voffB); PG8_STAGE(PG8_SA(0, 0), a2, voffA);
.LBB0_790:
	s_add_u32 s14, s12, 0xfff80080
	s_addc_u32 s15, s13, -1
	s_add_i32 s36, 0, 0x10000
	s_cmp_eq_u32 s35, 28
	s_cselect_b32 s17, s7, s15
	s_cselect_b32 s16, s30, s14
	s_cselect_b32 s15, s5, s34
	s_cselect_b32 s14, s31, s33
	s_add_i32 s40, 0, 0x14000
	v_add_u32_e32 v140, s36, v190
	v_add_u32_e32 v156, s40, v190
	ds_read_b128 v[120:123], v140
	ds_read_b128 v[128:131], v140 offset:1024
	ds_read_b128 v[132:135], v140 offset:2048
	ds_read_b128 v[140:143], v140 offset:3072
	ds_read_b128 v[144:147], v156
	ds_read_b128 v[148:151], v156 offset:1024
	ds_read_b128 v[152:155], v156 offset:2048
	ds_read_b128 v[156:159], v156 offset:3072
	v_lshl_add_u64 v[194:195], s[12:13], 0, v[174:175]
	s_add_i32 m0, s19, 0xc000
	ds_read_b128 v[178:181], v191
	ds_read_b128 v[182:185], v191 offset:1024
	ds_read_b128 v[186:189], v191 offset:2048
	ds_read_b128 v[206:209], v191 offset:3072
	ds_read_b128 v[210:213], v191 offset:4096
	ds_read_b128 v[214:217], v191 offset:5120
	ds_read_b128 v[218:221], v191 offset:6144
	ds_read_b128 v[222:225], v191 offset:7168
	global_load_lds_dwordx4 v[194:195], off
	v_lshl_add_u64 v[194:195], s[12:13], 0, v[176:177]
	s_add_i32 m0, s19, 0xe000
	s_nop 0
	global_load_lds_dwordx4 v[194:195], off
	s_waitcnt vmcnt(8)
	s_waitcnt lgkmcnt(0)
	s_barrier
	s_waitcnt lgkmcnt(0)
	v_mfma_f32_16x16x32_bf16 v[136:139], v[120:123], v[178:181], v[136:139]
	v_mfma_f32_16x16x32_bf16 v[124:127], v[132:135], v[178:181], v[124:127]
	v_mfma_f32_16x16x32_bf16 v[108:111], v[120:123], v[186:189], v[108:111]
	v_mfma_f32_16x16x32_bf16 v[104:107], v[132:135], v[186:189], v[104:107]
	v_mfma_f32_16x16x32_bf16 v[92:95], v[120:123], v[210:213], v[92:95]
	v_mfma_f32_16x16x32_bf16 v[88:91], v[132:135], v[210:213], v[88:91]
	v_mfma_f32_16x16x32_bf16 v[76:79], v[120:123], v[218:221], v[76:79]
	v_mfma_f32_16x16x32_bf16 v[72:75], v[132:135], v[218:221], v[72:75]
	v_mfma_f32_16x16x32_bf16 v[136:139], v[128:131], v[182:185], v[136:139]
	v_mfma_f32_16x16x32_bf16 v[124:127], v[140:143], v[182:185], v[124:127]
	v_mfma_f32_16x16x32_bf16 v[108:111], v[128:131], v[206:209], v[108:111]
	v_mfma_f32_16x16x32_bf16 v[104:107], v[140:143], v[206:209], v[104:107]
	v_mfma_f32_16x16x32_bf16 v[92:95], v[128:131], v[214:217], v[92:95]
	v_mfma_f32_16x16x32_bf16 v[88:91], v[140:143], v[214:217], v[88:91]
	v_mfma_f32_16x16x32_bf16 v[76:79], v[128:131], v[222:225], v[76:79]
	v_mfma_f32_16x16x32_bf16 v[72:75], v[140:143], v[222:225], v[72:75]
	v_mfma_f32_16x16x32_bf16 v[116:119], v[144:147], v[178:181], v[116:119]
	v_mfma_f32_16x16x32_bf16 v[112:115], v[152:155], v[178:181], v[112:115]
	v_mfma_f32_16x16x32_bf16 v[100:103], v[144:147], v[186:189], v[100:103]
	v_mfma_f32_16x16x32_bf16 v[96:99], v[152:155], v[186:189], v[96:99]
	v_mfma_f32_16x16x32_bf16 v[84:87], v[144:147], v[210:213], v[84:87]
	v_mfma_f32_16x16x32_bf16 v[80:83], v[152:155], v[210:213], v[80:83]
	v_mfma_f32_16x16x32_bf16 v[68:71], v[144:147], v[218:221], v[68:71]
	v_mfma_f32_16x16x32_bf16 v[64:67], v[152:155], v[218:221], v[64:67]
	v_mfma_f32_16x16x32_bf16 v[116:119], v[148:151], v[182:185], v[116:119]
	v_mfma_f32_16x16x32_bf16 v[112:115], v[156:159], v[182:185], v[112:115]
	v_mfma_f32_16x16x32_bf16 v[100:103], v[148:151], v[206:209], v[100:103]
	v_mfma_f32_16x16x32_bf16 v[96:99], v[156:159], v[206:209], v[96:99]
	v_mfma_f32_16x16x32_bf16 v[84:87], v[148:151], v[214:217], v[84:87]
	v_mfma_f32_16x16x32_bf16 v[80:83], v[156:159], v[214:217], v[80:83]
	v_mfma_f32_16x16x32_bf16 v[68:71], v[148:151], v[222:225], v[68:71]
	v_mfma_f32_16x16x32_bf16 v[64:67], v[156:159], v[222:225], v[64:67]
	s_barrier
	s_add_i32 s36, s36, s18
	v_lshl_add_u64 v[194:195], s[14:15], 0, v[164:165]
	s_mov_b32 m0, s36
	ds_read_b128 v[178:181], v191 offset:16384
	ds_read_b128 v[182:185], v191 offset:17408
	ds_read_b128 v[186:189], v191 offset:18432
	ds_read_b128 v[206:209], v191 offset:19456
	ds_read_b128 v[210:213], v191 offset:20480
	ds_read_b128 v[214:217], v191 offset:21504
	ds_read_b128 v[218:221], v191 offset:22528
	ds_read_b128 v[222:225], v191 offset:23552
	global_load_lds_dwordx4 v[194:195], off
	s_add_i32 m0, s36, 0x2000
	s_add_u32 s36, s14, 0x80000
	v_lshl_add_u64 v[196:197], s[14:15], 0, v[160:161]
	s_addc_u32 s37, s15, 0
	s_add_i32 s40, s40, s18
	global_load_lds_dwordx4 v[196:197], off
	v_lshl_add_u64 v[226:227], s[36:37], 0, v[164:165]
	s_mov_b32 m0, s40
	v_lshl_add_u64 v[228:229], s[16:17], 0, v[162:163]
	global_load_lds_dwordx4 v[226:227], off
	v_lshl_add_u64 v[226:227], s[36:37], 0, v[160:161]
	s_add_i32 m0, s40, 0x2000
	s_nop 0
	global_load_lds_dwordx4 v[226:227], off
	v_lshl_add_u64 v[226:227], s[16:17], 0, v[166:167]
	s_mov_b32 m0, s19
	s_nop 0
	global_load_lds_dwordx4 v[226:227], off
	s_mov_b32 m0, s20
	s_nop 0
	global_load_lds_dwordx4 v[228:229], off
	s_waitcnt vmcnt(8)
	s_waitcnt lgkmcnt(0)
	s_barrier
; #define PG8_STAGE(bufoff, gbase, voff) do { _Pragma("unroll") for (int _i = 0; _i < 2; ++_i) \
;         __builtin_amdgcn_global_load_lds((const unsigned*)((const char*)(gbase) + (voff)[_i]), (LAS unsigned*)(lds + (bufoff) + ldsw + _i * 8192), 16, 0, 0); } while (0)
; #define PG8_LDA(dst, b, h) do { _Pragma("unroll") for (int m = 0; m < 4; ++m) _Pragma("unroll") for (int k = 0; k < 2; ++k) dst[m][k] = *(const LAS bf16x8*)(lds + PG8_SA(b, h) + aoff + m * 2048 + k * 1024); } while (0)
; #define PG8_LDB(dst, b, h) do { _Pragma("unroll") for (int n = 0; n < 2; ++n) _Pragma("unroll") for (int k = 0; k < 2; ++k) dst[n][k] = *(const LAS bf16x8*)(lds + PG8_SB(b, h) + boff + n * 2048 + k * 1024); } while (0)
; #define PG8_MMA(ai, bj, At, Bt) do { __builtin_amdgcn_s_setprio(1); _Pragma("unroll") for (int m = 0; m < 4; ++m) _Pragma("unroll") for (int n = 0; n < 2; ++n) _Pragma("unroll") for (int k = 0; k < 2; ++k) \
;         acc[ai][bj][m][n] = __builtin_amdgcn_mfma_f32_16x16x32_bf16(Bt[n][k], At[m][k], acc[ai][bj][m][n], 0, 0, 0); __builtin_amdgcn_s_setprio(0); } while (0)
; #define PG8_WAIT_V(n) asm volatile("s_waitcnt vmcnt(" #n ")" ::: "memory")
; #define PG8_WAIT_L(n) asm volatile("s_waitcnt lgkmcnt(" #n ")" ::: "memory")
; #define PG8_BAR __builtin_amdgcn_s_barrier()
; #define PG8_SCHED __builtin_amdgcn_sched_barrier(0)
; template <class Epi, bool PERMA = false, bool DUAL = false, bool ALIGN_EPI = true, bool SP2 = true>
; __device__ __forceinline__ void gemm_phase(LAS unsigned char* lds, const Gemm g, const StaticOrder& S, const Epi& E) {
;     ...
;             PG8_WAIT_V(8); PG8_WAIT_L(0); PG8_BAR; PG8_MMA(1, 0, At, B0); PG8_MMA(1, 1, At, B1); PG8_BAR; PG8_SCHED;
;             PG8_LDB(B0, 1, 0); PG8_LDB(B1, 1, 1); PG8_SCHED; PG8_LDA(At, 1, 0); PG8_STAGE(PG8_SA(0, 1), a2 + hstepA, voffA);
;             PG8_WAIT_V(8); PG8_WAIT_L(0); PG8_BAR; PG8_MMA(0, 0, At, B0); PG8_MMA(0, 1, At, B1); PG8_BAR; PG8_SCHED;
	s_waitcnt lgkmcnt(0)
	v_mfma_f32_16x16x32_bf16 v[60:63], v[120:123], v[178:181], v[60:63]
	v_mfma_f32_16x16x32_bf16 v[56:59], v[132:135], v[178:181], v[56:59]
	v_mfma_f32_16x16x32_bf16 v[44:47], v[120:123], v[186:189], v[44:47]
	v_mfma_f32_16x16x32_bf16 v[40:43], v[132:135], v[186:189], v[40:43]
	v_mfma_f32_16x16x32_bf16 v[28:31], v[120:123], v[210:213], v[28:31]
	v_mfma_f32_16x16x32_bf16 v[24:27], v[132:135], v[210:213], v[24:27]
	v_mfma_f32_16x16x32_bf16 v[12:15], v[120:123], v[218:221], v[12:15]
	v_mfma_f32_16x16x32_bf16 v[8:11], v[132:135], v[218:221], v[8:11]
	v_mfma_f32_16x16x32_bf16 v[60:63], v[128:131], v[182:185], v[60:63]
	v_mfma_f32_16x16x32_bf16 v[56:59], v[140:143], v[182:185], v[56:59]
	v_mfma_f32_16x16x32_bf16 v[44:47], v[128:131], v[206:209], v[44:47]
	v_mfma_f32_16x16x32_bf16 v[40:43], v[140:143], v[206:209], v[40:43]
	v_mfma_f32_16x16x32_bf16 v[28:31], v[128:131], v[214:217], v[28:31]
	v_mfma_f32_16x16x32_bf16 v[24:27], v[140:143], v[214:217], v[24:27]
	v_mfma_f32_16x16x32_bf16 v[12:15], v[128:131], v[222:225], v[12:15]
	v_mfma_f32_16x16x32_bf16 v[8:11], v[140:143], v[222:225], v[8:11]
	v_mfma_f32_16x16x32_bf16 v[52:55], v[144:147], v[178:181], v[52:55]
	v_mfma_f32_16x16x32_bf16 v[48:51], v[152:155], v[178:181], v[48:51]
	v_mfma_f32_16x16x32_bf16 v[36:39], v[144:147], v[186:189], v[36:39]
	v_mfma_f32_16x16x32_bf16 v[32:35], v[152:155], v[186:189], v[32:35]
	v_mfma_f32_16x16x32_bf16 v[20:23], v[144:147], v[210:213], v[20:23]
	v_mfma_f32_16x16x32_bf16 v[16:19], v[152:155], v[210:213], v[16:19]
	v_mfma_f32_16x16x32_bf16 v[0:3], v[144:147], v[218:221], v[0:3]
	v_mfma_f32_16x16x32_bf16 v[4:7], v[152:155], v[218:221], v[4:7]
	v_mfma_f32_16x16x32_bf16 v[52:55], v[148:151], v[182:185], v[52:55]
	v_mfma_f32_16x16x32_bf16 v[48:51], v[156:159], v[182:185], v[48:51]
	v_mfma_f32_16x16x32_bf16 v[36:39], v[148:151], v[206:209], v[36:39]
	v_mfma_f32_16x16x32_bf16 v[32:35], v[156:159], v[206:209], v[32:35]
	v_mfma_f32_16x16x32_bf16 v[20:23], v[148:151], v[214:217], v[20:23]
	v_mfma_f32_16x16x32_bf16 v[16:19], v[156:159], v[214:217], v[16:19]
	v_mfma_f32_16x16x32_bf16 v[0:3], v[148:151], v[222:225], v[0:3]
	v_mfma_f32_16x16x32_bf16 v[4:7], v[156:159], v[222:225], v[4:7]
	s_barrier
	s_add_i32 s36, 0, 0x18000
	s_add_i32 s37, 0, 0x1c000
	v_add_u32_e32 v140, s36, v190
	v_add_u32_e32 v156, s37, v190
	ds_read_b128 v[120:123], v140
	ds_read_b128 v[128:131], v140 offset:1024
	ds_read_b128 v[132:135], v140 offset:2048
	ds_read_b128 v[140:143], v140 offset:3072
	ds_read_b128 v[144:147], v156
	ds_read_b128 v[148:151], v156 offset:1024
	ds_read_b128 v[152:155], v156 offset:2048
	ds_read_b128 v[156:159], v156 offset:3072
	s_add_u32 s16, s16, 0x80000
	s_addc_u32 s17, s17, 0
	s_mov_b32 m0, s21
	v_lshl_add_u64 v[238:239], s[16:17], 0, v[166:167]
	ds_read_b128 v[178:181], v191 offset:32768
	ds_read_b128 v[182:185], v191 offset:33792
	ds_read_b128 v[186:189], v191 offset:34816
	ds_read_b128 v[206:209], v191 offset:35840
	ds_read_b128 v[210:213], v191 offset:36864
	ds_read_b128 v[214:217], v191 offset:37888
	ds_read_b128 v[218:221], v191 offset:38912
	ds_read_b128 v[222:225], v191 offset:39936
	global_load_lds_dwordx4 v[238:239], off
	v_lshl_add_u64 v[238:239], s[16:17], 0, v[162:163]
	s_mov_b32 m0, s22
	s_nop 0
	global_load_lds_dwordx4 v[238:239], off
	s_waitcnt vmcnt(8)
	s_waitcnt lgkmcnt(0)
	s_barrier
	s_waitcnt lgkmcnt(0)
	v_mfma_f32_16x16x32_bf16 v[136:139], v[120:123], v[178:181], v[136:139]
	v_mfma_f32_16x16x32_bf16 v[124:127], v[132:135], v[178:181], v[124:127]
	v_mfma_f32_16x16x32_bf16 v[108:111], v[120:123], v[186:189], v[108:111]
	v_mfma_f32_16x16x32_bf16 v[104:107], v[132:135], v[186:189], v[104:107]
	v_mfma_f32_16x16x32_bf16 v[92:95], v[120:123], v[210:213], v[92:95]
	v_mfma_f32_16x16x32_bf16 v[88:91], v[132:135], v[210:213], v[88:91]
	v_mfma_f32_16x16x32_bf16 v[76:79], v[120:123], v[218:221], v[76:79]
	v_mfma_f32_16x16x32_bf16 v[72:75], v[132:135], v[218:221], v[72:75]
	v_mfma_f32_16x16x32_bf16 v[136:139], v[128:131], v[182:185], v[136:139]
	v_mfma_f32_16x16x32_bf16 v[124:127], v[140:143], v[182:185], v[124:127]
	v_mfma_f32_16x16x32_bf16 v[108:111], v[128:131], v[206:209], v[108:111]
	v_mfma_f32_16x16x32_bf16 v[104:107], v[140:143], v[206:209], v[104:107]
	v_mfma_f32_16x16x32_bf16 v[92:95], v[128:131], v[214:217], v[92:95]
	v_mfma_f32_16x16x32_bf16 v[88:91], v[140:143], v[214:217], v[88:91]
	v_mfma_f32_16x16x32_bf16 v[76:79], v[128:131], v[222:225], v[76:79]
	v_mfma_f32_16x16x32_bf16 v[72:75], v[140:143], v[222:225], v[72:75]
	v_mfma_f32_16x16x32_bf16 v[116:119], v[144:147], v[178:181], v[116:119]
	v_mfma_f32_16x16x32_bf16 v[112:115], v[152:155], v[178:181], v[112:115]
	v_mfma_f32_16x16x32_bf16 v[100:103], v[144:147], v[186:189], v[100:103]
	v_mfma_f32_16x16x32_bf16 v[96:99], v[152:155], v[186:189], v[96:99]
	v_mfma_f32_16x16x32_bf16 v[84:87], v[144:147], v[210:213], v[84:87]
	v_mfma_f32_16x16x32_bf16 v[80:83], v[152:155], v[210:213], v[80:83]
	v_mfma_f32_16x16x32_bf16 v[68:71], v[144:147], v[218:221], v[68:71]
	v_mfma_f32_16x16x32_bf16 v[64:67], v[152:155], v[218:221], v[64:67]
	v_mfma_f32_16x16x32_bf16 v[116:119], v[148:151], v[182:185], v[116:119]
	v_mfma_f32_16x16x32_bf16 v[112:115], v[156:159], v[182:185], v[112:115]
	v_mfma_f32_16x16x32_bf16 v[100:103], v[148:151], v[206:209], v[100:103]
	v_mfma_f32_16x16x32_bf16 v[96:99], v[156:159], v[206:209], v[96:99]
	v_mfma_f32_16x16x32_bf16 v[84:87], v[148:151], v[214:217], v[84:87]
	v_mfma_f32_16x16x32_bf16 v[80:83], v[156:159], v[214:217], v[80:83]
	v_mfma_f32_16x16x32_bf16 v[68:71], v[148:151], v[222:225], v[68:71]
	v_mfma_f32_16x16x32_bf16 v[64:67], v[156:159], v[222:225], v[64:67]
	s_barrier
; #define PG8_STAGE(bufoff, gbase, voff) do { _Pragma("unroll") for (int _i = 0; _i < 2; ++_i) \
;         __builtin_amdgcn_global_load_lds((const unsigned*)((const char*)(gbase) + (voff)[_i]), (LAS unsigned*)(lds + (bufoff) + ldsw + _i * 8192), 16, 0, 0); } while (0)
; #define PG8_LDA(dst, b, h) do { _Pragma("unroll") for (int m = 0; m < 4; ++m) _Pragma("unroll") for (int k = 0; k < 2; ++k) dst[m][k] = *(const LAS bf16x8*)(lds + PG8_SA(b, h) + aoff + m * 2048 + k * 1024); } while (0)
; #define PG8_MMA(ai, bj, At, Bt) do { __builtin_amdgcn_s_setprio(1); _Pragma("unroll") for (int m = 0; m < 4; ++m) _Pragma("unroll") for (int n = 0; n < 2; ++n) _Pragma("unroll") for (int k = 0; k < 2; ++k) \
;         acc[ai][bj][m][n] = __builtin_amdgcn_mfma_f32_16x16x32_bf16(Bt[n][k], At[m][k], acc[ai][bj][m][n], 0, 0, 0); __builtin_amdgcn_s_setprio(0); } while (0)
; #define PG8_WAIT_V(n) asm volatile("s_waitcnt vmcnt(" #n ")" ::: "memory")
; #define PG8_WAIT_L(n) asm volatile("s_waitcnt lgkmcnt(" #n ")" ::: "memory")
; #define PG8_BAR __builtin_amdgcn_s_barrier()
; #define PG8_SCHED __builtin_amdgcn_sched_barrier(0)
; template <class Epi, bool PERMA = false, bool DUAL = false, bool ALIGN_EPI = true, bool SP2 = true>
; __device__ __forceinline__ void gemm_phase(LAS unsigned char* lds, const Gemm g, const StaticOrder& S, const Epi& E) {
;     ...
;             PG8_LDA(At, 1, 1); PG8_STAGE(PG8_SB(1, 0), b3, voffB); PG8_STAGE(PG8_SB(1, 1), b3 + hstepB, voffB); PG8_STAGE(PG8_SA(1, 0), a3, voffA);
;             PG8_WAIT_V(8); PG8_WAIT_L(0); PG8_BAR; PG8_MMA(1, 0, At, B0); PG8_MMA(1, 1, At, B1); PG8_BAR; PG8_SCHED;
;     ...
;         if constexpr (ALIGN_EPI) { if (wr == 0) PG8_BAR; }
	s_add_i32 s16, s36, s18
	v_lshl_add_u64 v[194:195], v[194:195], 0, s[46:47]
	s_mov_b32 m0, s16
	ds_read_b128 v[178:181], v191 offset:49152
	ds_read_b128 v[182:185], v191 offset:50176
	ds_read_b128 v[186:189], v191 offset:51200
	ds_read_b128 v[206:209], v191 offset:52224
	ds_read_b128 v[210:213], v191 offset:53248
	ds_read_b128 v[214:217], v191 offset:54272
	ds_read_b128 v[218:221], v191 offset:55296
	ds_read_b128 v[222:225], v191 offset:56320
	global_load_lds_dwordx4 v[194:195], off
	s_add_i32 m0, s16, 0x2000
	s_add_u32 s14, s14, 0x80080
	v_lshl_add_u64 v[194:195], v[196:197], 0, s[46:47]
	s_addc_u32 s15, s15, 0
	s_add_i32 s16, s37, s18
	global_load_lds_dwordx4 v[194:195], off
	v_lshl_add_u64 v[194:195], s[14:15], 0, v[164:165]
	s_mov_b32 m0, s16
	s_nop 0
	global_load_lds_dwordx4 v[194:195], off
	v_lshl_add_u64 v[194:195], s[14:15], 0, v[160:161]
	s_add_i32 m0, s16, 0x2000
	s_nop 0
	global_load_lds_dwordx4 v[194:195], off
	v_lshl_add_u64 v[194:195], v[226:227], 0, s[46:47]
	s_mov_b32 m0, s25
	s_nop 0
	global_load_lds_dwordx4 v[194:195], off
	v_lshl_add_u64 v[194:195], v[228:229], 0, s[46:47]
	s_mov_b32 m0, s26
	s_nop 0
	global_load_lds_dwordx4 v[194:195], off
	s_waitcnt vmcnt(8)
	s_waitcnt lgkmcnt(0)
	s_barrier
	s_waitcnt lgkmcnt(0)
	v_mfma_f32_16x16x32_bf16 v[60:63], v[120:123], v[178:181], v[60:63]
	v_mfma_f32_16x16x32_bf16 v[56:59], v[132:135], v[178:181], v[56:59]
	v_mfma_f32_16x16x32_bf16 v[44:47], v[120:123], v[186:189], v[44:47]
	v_mfma_f32_16x16x32_bf16 v[40:43], v[132:135], v[186:189], v[40:43]
	v_mfma_f32_16x16x32_bf16 v[28:31], v[120:123], v[210:213], v[28:31]
	v_mfma_f32_16x16x32_bf16 v[24:27], v[132:135], v[210:213], v[24:27]
	v_mfma_f32_16x16x32_bf16 v[12:15], v[120:123], v[218:221], v[12:15]
	v_mfma_f32_16x16x32_bf16 v[8:11], v[132:135], v[218:221], v[8:11]
	v_mfma_f32_16x16x32_bf16 v[60:63], v[128:131], v[182:185], v[60:63]
	v_mfma_f32_16x16x32_bf16 v[56:59], v[140:143], v[182:185], v[56:59]
	v_mfma_f32_16x16x32_bf16 v[44:47], v[128:131], v[206:209], v[44:47]
	v_mfma_f32_16x16x32_bf16 v[40:43], v[140:143], v[206:209], v[40:43]
	v_mfma_f32_16x16x32_bf16 v[28:31], v[128:131], v[214:217], v[28:31]
	v_mfma_f32_16x16x32_bf16 v[24:27], v[140:143], v[214:217], v[24:27]
	v_mfma_f32_16x16x32_bf16 v[12:15], v[128:131], v[222:225], v[12:15]
	v_mfma_f32_16x16x32_bf16 v[8:11], v[140:143], v[222:225], v[8:11]
	v_mfma_f32_16x16x32_bf16 v[52:55], v[144:147], v[178:181], v[52:55]
	v_mfma_f32_16x16x32_bf16 v[48:51], v[152:155], v[178:181], v[48:51]
	v_mfma_f32_16x16x32_bf16 v[36:39], v[144:147], v[186:189], v[36:39]
	v_mfma_f32_16x16x32_bf16 v[32:35], v[152:155], v[186:189], v[32:35]
	v_mfma_f32_16x16x32_bf16 v[20:23], v[144:147], v[210:213], v[20:23]
	v_mfma_f32_16x16x32_bf16 v[16:19], v[152:155], v[210:213], v[16:19]
	v_mfma_f32_16x16x32_bf16 v[0:3], v[144:147], v[218:221], v[0:3]
	v_mfma_f32_16x16x32_bf16 v[4:7], v[152:155], v[218:221], v[4:7]
	v_mfma_f32_16x16x32_bf16 v[52:55], v[148:151], v[182:185], v[52:55]
	v_mfma_f32_16x16x32_bf16 v[48:51], v[156:159], v[182:185], v[48:51]
	v_mfma_f32_16x16x32_bf16 v[36:39], v[148:151], v[206:209], v[36:39]
	v_mfma_f32_16x16x32_bf16 v[32:35], v[156:159], v[206:209], v[32:35]
	v_mfma_f32_16x16x32_bf16 v[20:23], v[148:151], v[214:217], v[20:23]
	v_mfma_f32_16x16x32_bf16 v[16:19], v[156:159], v[214:217], v[16:19]
	v_mfma_f32_16x16x32_bf16 v[0:3], v[148:151], v[222:225], v[0:3]
	v_mfma_f32_16x16x32_bf16 v[4:7], v[156:159], v[222:225], v[4:7]
	s_add_i32 s35, s35, 2
	s_add_u32 s12, s12, 0x100
	s_addc_u32 s13, s13, 0
	s_add_u32 s33, s33, 0x100
	s_addc_u32 s34, s34, 0
	s_cmp_gt_u32 s35, 29
	s_barrier
	s_cbranch_scc0 .LBB0_790
	s_and_b64 vcc, exec, s[2:3]
	s_cbranch_vccz .LBB0_793
	s_barrier
